# plus residual epilogues reduce row sums with permlane16/32 swaps instead of ds_bpermute round trips
# baseline (speedup 1.0000x reference)
; #define LAS __attribute__((address_space(3)))
; __device__ __forceinline__ unsigned cvt_pk_bf16(float lo, float hi) { unsigned r; asm volatile("v_cvt_pk_bf16_f32 %0, %1, %2" : "=v"(r) : "v"(lo), "v"(hi)); return r; }
; #define EPR_LOAD(IT, BUF) do { const unsigned row_ = rb + 128 * ((IT) >> 2) + 16 * ((IT) & 3); _Pragma("unroll") for (int bj = 0; bj < 2; ++bj) \
;             xin[BUF][bj] = *(const u32x4*)(XG + (row_ * DM + cbase + bj * 128)); } while (0)
;     __device__ __forceinline__ void operator()(f32x4 (&acc)[2][2][4][2], const Unit& u, int ui, int wr, int wc, int fr, int fq, int lane, LAS unsigned char* lds) const {
;     ...
;         const unsigned cbase = (unsigned)(u.pn * 256 + wc * 32 + 8 * fq), rb = (unsigned)(u.pm * 256 + 64 * wr + fr);
;         LAS float* red = (LAS float*)(lds + EXTRA_OFF);
;         u32x4 xin[2][2];
;     ...
;         EPR_LOAD(0, 0);
; #pragma unroll
;         for (int it = 0; it < 8; ++it) {
;             if (it + 1 < 8) EPR_LOAD(it + 1, (it + 1) & 1);
;             __builtin_amdgcn_sched_barrier(0);
;             const int ai = it >> 2, m = it & 3;
;             const unsigned row = rb + 128 * ai + 16 * m;
;             float ss = 0.f;
; #pragma unroll
;             for (int bj = 0; bj < 2; ++bj) {
;                 const u32x4 xw = xin[it & 1][bj];
;                 f32x4 v0, v1;
;                 v0[0] = __builtin_bit_cast(float, xw.x << 16); v0[1] = __builtin_bit_cast(float, xw.x & 0xffff0000u); v0[2] = __builtin_bit_cast(float, xw.y << 16); v0[3] = __builtin_bit_cast(float, xw.y & 0xffff0000u);
;                 v1[0] = __builtin_bit_cast(float, xw.z << 16); v1[1] = __builtin_bit_cast(float, xw.z & 0xffff0000u); v1[2] = __builtin_bit_cast(float, xw.w << 16); v1[3] = __builtin_bit_cast(float, xw.w & 0xffff0000u);
;                 v0 += acc[ai][bj][m][0]; v1 += acc[ai][bj][m][1];
;                 ss += ((v0[0] * v0[0] + v0[1] * v0[1]) + (v0[2] * v0[2] + v0[3] * v0[3])) + ((v1[0] * v1[0] + v1[1] * v1[1]) + (v1[2] * v1[2] + v1[3] * v1[3]));
;                 u32x4 w; w.x = cvt_pk_bf16(v0[0], v0[1]); w.y = cvt_pk_bf16(v0[2], v0[3]); w.z = cvt_pk_bf16(v1[0], v1[1]); w.w = cvt_pk_bf16(v1[2], v1[3]);
;                 *(u32x4*)(XG + (row * DM + cbase + bj * 128)) = w;
;             }
;             ss += __shfl_xor(ss, 16); ss += __shfl_xor(ss, 32);
;             if (fq == 0) red[(128 * ai + 64 * wr + 16 * m + fr) * 4 + wc] = ss;
.LBB0_646:
	v_mov_b32_e32 v130, v142
	v_mov_b32_e32 v128, v140
	v_mov_b32_e32 v143, v141
	s_lshl_b32 s0, s40, 8
	s_lshl_b32 s1, s2, 18
	v_add_u32_e32 v160, s51, v128
	s_or_b32 s0, s0, s53
	v_lshlrev_b32_e32 v129, 3, v130
	v_lshlrev_b32_e32 v128, 10, v160
	s_add_i32 s0, s0, s1
	v_add3_u32 v188, s0, v129, v128
	v_add_u32_e32 v128, 0x80, v188
	v_mov_b32_e32 v129, v189
	v_lshl_add_u64 v[154:155], v[128:129], 1, s[8:9]
	v_add_u32_e32 v128, 0x4000, v188
	v_lshl_add_u64 v[136:137], v[128:129], 1, s[8:9]
	v_add_u32_e32 v128, 0x4080, v188
	v_lshl_add_u64 v[138:139], v[128:129], 1, s[8:9]
	v_lshl_add_u64 v[152:153], v[188:189], 1, s[8:9]
	v_cmp_eq_u32_e32 vcc, 0, v130
	global_load_dwordx4 v[132:135], v[136:137], off
	global_load_dwordx4 v[128:131], v[138:139], off
	global_load_dwordx4 v[144:147], v[152:153], off
	global_load_dwordx4 v[148:151], v[154:155], off
	s_mov_b32 s99, 0
	s_mov_b32 s98, 0x10000
	v_lshl_add_u64 v[186:187], v[152:153], 0, s[98:99]
	global_load_dwordx4 v[162:165], v[186:187], off
	global_load_dwordx4 v[166:169], v[186:187], off offset:256
	s_mov_b32 s98, 0x18000
	v_lshl_add_u64 v[186:187], v[152:153], 0, s[98:99]
	global_load_dwordx4 v[170:173], v[186:187], off
	global_load_dwordx4 v[174:177], v[186:187], off offset:256
	s_mov_b32 s98, 0x40000
	v_lshl_add_u64 v[186:187], v[152:153], 0, s[98:99]
	global_load_dwordx4 v[178:181], v[186:187], off
	global_load_dwordx4 v[182:185], v[186:187], off offset:256
	s_mov_b32 s98, 0x48000
	v_lshl_add_u64 v[186:187], v[152:153], 0, s[98:99]
	global_load_dwordx4 v[194:197], v[186:187], off
	global_load_dwordx4 v[198:201], v[186:187], off offset:256
	s_mov_b32 s98, 0x50000
	v_lshl_add_u64 v[186:187], v[152:153], 0, s[98:99]
	global_load_dwordx4 v[202:205], v[186:187], off
	global_load_dwordx4 v[212:215], v[186:187], off offset:256
	s_mov_b32 s98, 0x58000
	v_lshl_add_u64 v[186:187], v[152:153], 0, s[98:99]
	global_load_dwordx4 v[216:219], v[186:187], off
	global_load_dwordx4 v[220:223], v[186:187], off offset:256
	s_waitcnt vmcnt(12)
	v_lshlrev_b32_e32 v156, 16, v144
	v_and_b32_e32 v157, 0xffff0000, v144
	v_lshlrev_b32_e32 v144, 16, v145
	v_and_b32_e32 v145, 0xffff0000, v145
	v_lshlrev_b32_e32 v158, 16, v146
	v_and_b32_e32 v159, 0xffff0000, v146
	v_lshlrev_b32_e32 v146, 16, v147
	v_and_b32_e32 v147, 0xffff0000, v147
	v_pk_add_f32 v[126:127], v[126:127], v[144:145]
	v_pk_add_f32 v[124:125], v[124:125], v[156:157]
	v_pk_add_f32 v[144:145], v[122:123], v[146:147]
	v_pk_add_f32 v[122:123], v[120:121], v[158:159]
	v_mul_f32_e32 v120, v125, v125
	v_mul_f32_e32 v121, v127, v127
	v_fmac_f32_e32 v120, v124, v124
	v_fmac_f32_e32 v121, v126, v126
	v_add_f32_e32 v120, v120, v121
	v_mul_f32_e32 v121, v123, v123
	v_mul_f32_e32 v146, v145, v145
	v_fmac_f32_e32 v121, v122, v122
	v_fmac_f32_e32 v146, v144, v144
	v_add_f32_e32 v121, v121, v146
	v_add_f32_e32 v156, v120, v121
	v_cvt_pk_bf16_f32 v120, v124, v125
	v_cvt_pk_bf16_f32 v121, v126, v127
	v_lshlrev_b32_e32 v124, 16, v148
	v_and_b32_e32 v125, 0xffff0000, v148
	v_lshlrev_b32_e32 v126, 16, v149
	v_and_b32_e32 v127, 0xffff0000, v149
	v_lshlrev_b32_e32 v146, 16, v150
	v_and_b32_e32 v147, 0xffff0000, v150
	v_pk_add_f32 v[118:119], v[118:119], v[126:127]
	v_pk_add_f32 v[116:117], v[116:117], v[124:125]
	v_lshlrev_b32_e32 v148, 16, v151
	v_and_b32_e32 v149, 0xffff0000, v151
	v_pk_add_f32 v[146:147], v[112:113], v[146:147]
	v_mul_f32_e32 v112, v117, v117
	v_mul_f32_e32 v113, v119, v119
	v_pk_add_f32 v[148:149], v[114:115], v[148:149]
	v_fmac_f32_e32 v112, v116, v116
	v_fmac_f32_e32 v113, v118, v118
	v_add_f32_e32 v112, v112, v113
	v_mul_f32_e32 v113, v147, v147
	v_mul_f32_e32 v114, v149, v149
	v_fmac_f32_e32 v113, v146, v146
	v_fmac_f32_e32 v114, v148, v148
	v_add_f32_e32 v113, v113, v114
	v_and_b32_e32 v114, 64, v208
	v_add_f32_e32 v112, v112, v113
	v_xor_b32_e32 v113, 16, v208
	v_add_u32_e32 v124, 64, v114
	v_cmp_lt_i32_e64 s[4:5], v113, v124
	v_add_f32_e32 v112, v156, v112
	v_cvt_pk_bf16_f32 v122, v122, v123
	v_cvt_pk_bf16_f32 v123, v144, v145
	global_store_dwordx4 v[152:153], v[120:123], off
	v_cndmask_b32_e64 v113, v208, v113, s[4:5]
	v_lshlrev_b32_e32 v125, 2, v113
	v_mov_b32_e32 v113, v112
	s_nop 1
	v_permlane16_swap_b32 v113, v112
	v_cvt_pk_bf16_f32 v114, v116, v117
	v_cvt_pk_bf16_f32 v115, v118, v119
	v_cvt_pk_bf16_f32 v116, v146, v147
	v_cvt_pk_bf16_f32 v117, v148, v149
	s_waitcnt lgkmcnt(0)
	v_add_f32_e32 v112, v112, v113
	v_xor_b32_e32 v113, 32, v208
	v_cmp_lt_i32_e64 s[4:5], v113, v124
	v_lshl_add_u32 v124, v160, 4, s64
	global_store_dwordx4 v[154:155], v[114:117], off
	v_cndmask_b32_e64 v113, v208, v113, s[4:5]
	v_lshlrev_b32_e32 v126, 2, v113
	v_mov_b32_e32 v113, v112
	s_nop 1
	v_permlane32_swap_b32 v113, v112
	s_and_saveexec_b64 s[4:5], vcc
	s_cbranch_execz .LBB0_648
	s_waitcnt lgkmcnt(0)
	v_add_f32_e32 v112, v112, v113
	ds_write_b32 v124, v112
; __device__ __forceinline__ unsigned cvt_pk_bf16(float lo, float hi) { unsigned r; asm volatile("v_cvt_pk_bf16_f32 %0, %1, %2" : "=v"(r) : "v"(lo), "v"(hi)); return r; }
; #define EPR_LOAD(IT, BUF) do { const unsigned row_ = rb + 128 * ((IT) >> 2) + 16 * ((IT) & 3); _Pragma("unroll") for (int bj = 0; bj < 2; ++bj) \
;             xin[BUF][bj] = *(const u32x4*)(XG + (row_ * DM + cbase + bj * 128)); } while (0)
;     __device__ __forceinline__ void operator()(f32x4 (&acc)[2][2][4][2], const Unit& u, int ui, int wr, int wc, int fr, int fq, int lane, LAS unsigned char* lds) const {
;     ...
;         EPR_LOAD(0, 0);
; #pragma unroll
;         for (int it = 0; it < 8; ++it) {
;             if (it + 1 < 8) EPR_LOAD(it + 1, (it + 1) & 1);
;             __builtin_amdgcn_sched_barrier(0);
;             const int ai = it >> 2, m = it & 3;
;             const unsigned row = rb + 128 * ai + 16 * m;
;             float ss = 0.f;
; #pragma unroll
;             for (int bj = 0; bj < 2; ++bj) {
;                 const u32x4 xw = xin[it & 1][bj];
;                 f32x4 v0, v1;
;                 v0[0] = __builtin_bit_cast(float, xw.x << 16); v0[1] = __builtin_bit_cast(float, xw.x & 0xffff0000u); v0[2] = __builtin_bit_cast(float, xw.y << 16); v0[3] = __builtin_bit_cast(float, xw.y & 0xffff0000u);
;                 v1[0] = __builtin_bit_cast(float, xw.z << 16); v1[1] = __builtin_bit_cast(float, xw.z & 0xffff0000u); v1[2] = __builtin_bit_cast(float, xw.w << 16); v1[3] = __builtin_bit_cast(float, xw.w & 0xffff0000u);
;                 v0 += acc[ai][bj][m][0]; v1 += acc[ai][bj][m][1];
;                 ss += ((v0[0] * v0[0] + v0[1] * v0[1]) + (v0[2] * v0[2] + v0[3] * v0[3])) + ((v1[0] * v1[0] + v1[1] * v1[1]) + (v1[2] * v1[2] + v1[3] * v1[3]));
;                 u32x4 w; w.x = cvt_pk_bf16(v0[0], v0[1]); w.y = cvt_pk_bf16(v0[2], v0[3]); w.z = cvt_pk_bf16(v1[0], v1[1]); w.w = cvt_pk_bf16(v1[2], v1[3]);
;                 *(u32x4*)(XG + (row * DM + cbase + bj * 128)) = w;
;             }
;             ss += __shfl_xor(ss, 16); ss += __shfl_xor(ss, 32);
;             if (fq == 0) red[(128 * ai + 64 * wr + 16 * m + fr) * 4 + wc] = ss;
.LBB0_648:
	s_or_b64 exec, exec, s[4:5]
	v_add_u32_e32 v112, 0x8000, v188
	s_waitcnt lgkmcnt(0)
	v_mov_b32_e32 v113, v189
	v_lshl_add_u64 v[122:123], v[112:113], 1, s[8:9]
	v_add_u32_e32 v112, 0x8080, v188
	v_lshl_add_u64 v[120:121], v[112:113], 1, s[8:9]
	v_lshlrev_b32_e32 v144, 16, v132
	v_and_b32_e32 v145, 0xffff0000, v132
	v_lshlrev_b32_e32 v132, 16, v133
	v_and_b32_e32 v133, 0xffff0000, v133
	v_lshlrev_b32_e32 v146, 16, v134
	v_and_b32_e32 v147, 0xffff0000, v134
	v_lshlrev_b32_e32 v134, 16, v135
	v_and_b32_e32 v135, 0xffff0000, v135
	v_pk_add_f32 v[110:111], v[110:111], v[132:133]
	v_pk_add_f32 v[108:109], v[108:109], v[144:145]
	v_pk_add_f32 v[132:133], v[106:107], v[134:135]
	v_pk_add_f32 v[106:107], v[104:105], v[146:147]
	v_mul_f32_e32 v104, v109, v109
	v_mul_f32_e32 v105, v111, v111
	v_fmac_f32_e32 v104, v108, v108
	v_fmac_f32_e32 v105, v110, v110
	v_add_f32_e32 v104, v104, v105
	v_mul_f32_e32 v105, v107, v107
	v_mul_f32_e32 v127, v133, v133
	v_fmac_f32_e32 v105, v106, v106
	v_fmac_f32_e32 v127, v132, v132
	v_add_f32_e32 v105, v105, v127
	v_add_f32_e32 v127, v104, v105
	v_cvt_pk_bf16_f32 v104, v108, v109
	v_cvt_pk_bf16_f32 v105, v110, v111
	v_lshlrev_b32_e32 v108, 16, v128
	v_and_b32_e32 v109, 0xffff0000, v128
	v_lshlrev_b32_e32 v110, 16, v129
	v_and_b32_e32 v111, 0xffff0000, v129
	v_lshlrev_b32_e32 v128, 16, v130
	v_and_b32_e32 v129, 0xffff0000, v130
	v_pk_add_f32 v[102:103], v[102:103], v[110:111]
	v_pk_add_f32 v[100:101], v[100:101], v[108:109]
	v_lshlrev_b32_e32 v130, 16, v131
	v_and_b32_e32 v131, 0xffff0000, v131
	v_pk_add_f32 v[110:111], v[96:97], v[128:129]
	v_mul_f32_e32 v96, v101, v101
	v_mul_f32_e32 v97, v103, v103
	v_pk_add_f32 v[108:109], v[98:99], v[130:131]
	v_fmac_f32_e32 v96, v100, v100
	v_fmac_f32_e32 v97, v102, v102
	v_add_f32_e32 v96, v96, v97
	v_mul_f32_e32 v97, v111, v111
	v_mul_f32_e32 v98, v109, v109
	v_fmac_f32_e32 v97, v110, v110
	v_fmac_f32_e32 v98, v108, v108
	v_add_f32_e32 v97, v97, v98
	v_add_f32_e32 v96, v96, v97
	v_add_f32_e32 v96, v127, v96
	v_mov_b32_e32 v97, v96
	s_nop 1
	v_permlane16_swap_b32 v97, v96
	v_cvt_pk_bf16_f32 v106, v106, v107
	v_cvt_pk_bf16_f32 v107, v132, v133
	global_store_dwordx4 v[136:137], v[104:107], off
	v_cvt_pk_bf16_f32 v98, v100, v101
	s_waitcnt lgkmcnt(0)
	v_add_f32_e32 v96, v96, v97
	v_mov_b32_e32 v97, v96
	s_nop 1
	v_permlane32_swap_b32 v97, v96
	v_cvt_pk_bf16_f32 v99, v102, v103
	v_cvt_pk_bf16_f32 v100, v110, v111
	v_cvt_pk_bf16_f32 v101, v108, v109
	global_store_dwordx4 v[138:139], v[98:101], off
	s_and_saveexec_b64 s[4:5], vcc
	s_cbranch_execz .LBB0_650
	s_waitcnt lgkmcnt(0)
	v_add_f32_e32 v96, v96, v97
	ds_write_b32 v124, v96 offset:256
.LBB0_650:
	s_or_b64 exec, exec, s[4:5]
	v_add_u32_e32 v96, 0xc000, v188
	s_waitcnt lgkmcnt(0)
	v_mov_b32_e32 v97, v189
	v_lshl_add_u64 v[106:107], v[96:97], 1, s[8:9]
	v_add_u32_e32 v96, 0xc080, v188
	v_lshl_add_u64 v[104:105], v[96:97], 1, s[8:9]
	s_waitcnt vmcnt(15)
	v_lshlrev_b32_e32 v108, 16, v162
	v_and_b32_e32 v109, 0xffff0000, v162
	v_lshlrev_b32_e32 v110, 16, v163
	v_and_b32_e32 v111, 0xffff0000, v163
	v_lshlrev_b32_e32 v116, 16, v164
	v_and_b32_e32 v117, 0xffff0000, v164
	v_lshlrev_b32_e32 v118, 16, v165
	v_and_b32_e32 v119, 0xffff0000, v165
	v_pk_add_f32 v[94:95], v[94:95], v[110:111]
	v_pk_add_f32 v[92:93], v[92:93], v[108:109]
	v_pk_add_f32 v[108:109], v[90:91], v[118:119]
	v_pk_add_f32 v[90:91], v[88:89], v[116:117]
	v_mul_f32_e32 v88, v93, v93
	v_mul_f32_e32 v89, v95, v95
	v_fmac_f32_e32 v88, v92, v92
	v_fmac_f32_e32 v89, v94, v94
	v_add_f32_e32 v88, v88, v89
	v_mul_f32_e32 v89, v91, v91
	v_mul_f32_e32 v110, v109, v109
	v_fmac_f32_e32 v89, v90, v90
	v_fmac_f32_e32 v110, v108, v108
	v_add_f32_e32 v89, v89, v110
	v_add_f32_e32 v116, v88, v89
	v_cvt_pk_bf16_f32 v88, v92, v93
	v_cvt_pk_bf16_f32 v89, v94, v95
	s_waitcnt vmcnt(14)
	v_lshlrev_b32_e32 v92, 16, v166
	v_and_b32_e32 v93, 0xffff0000, v166
	v_lshlrev_b32_e32 v94, 16, v167
	v_and_b32_e32 v95, 0xffff0000, v167
	v_lshlrev_b32_e32 v110, 16, v168
	v_and_b32_e32 v111, 0xffff0000, v168
	v_pk_add_f32 v[86:87], v[86:87], v[94:95]
	v_pk_add_f32 v[84:85], v[84:85], v[92:93]
	v_lshlrev_b32_e32 v112, 16, v169
	v_and_b32_e32 v113, 0xffff0000, v169
	v_pk_add_f32 v[94:95], v[80:81], v[110:111]
	v_mul_f32_e32 v80, v85, v85
	v_mul_f32_e32 v81, v87, v87
	v_pk_add_f32 v[92:93], v[82:83], v[112:113]
	v_fmac_f32_e32 v80, v84, v84
	v_fmac_f32_e32 v81, v86, v86
	v_add_f32_e32 v80, v80, v81
	v_mul_f32_e32 v81, v95, v95
	v_mul_f32_e32 v82, v93, v93
	v_fmac_f32_e32 v81, v94, v94
	v_fmac_f32_e32 v82, v92, v92
	v_add_f32_e32 v81, v81, v82
	v_add_f32_e32 v80, v80, v81
	v_add_f32_e32 v80, v116, v80
	v_mov_b32_e32 v81, v80
	s_nop 1
	v_permlane16_swap_b32 v81, v80
	v_cvt_pk_bf16_f32 v90, v90, v91
	v_cvt_pk_bf16_f32 v91, v108, v109
	global_store_dwordx4 v[122:123], v[88:91], off
	v_cvt_pk_bf16_f32 v82, v84, v85
	s_waitcnt lgkmcnt(0)
	v_add_f32_e32 v80, v80, v81
	v_mov_b32_e32 v81, v80
	s_nop 1
	v_permlane32_swap_b32 v81, v80
	v_cvt_pk_bf16_f32 v83, v86, v87
	v_cvt_pk_bf16_f32 v84, v94, v95
	v_cvt_pk_bf16_f32 v85, v92, v93
	global_store_dwordx4 v[120:121], v[82:85], off
	s_and_saveexec_b64 s[4:5], vcc
	s_cbranch_execz .LBB0_652
	s_waitcnt lgkmcnt(0)
	v_add_f32_e32 v80, v80, v81
	ds_write_b32 v124, v80 offset:512
; __device__ __forceinline__ unsigned cvt_pk_bf16(float lo, float hi) { unsigned r; asm volatile("v_cvt_pk_bf16_f32 %0, %1, %2" : "=v"(r) : "v"(lo), "v"(hi)); return r; }
; #define EPR_LOAD(IT, BUF) do { const unsigned row_ = rb + 128 * ((IT) >> 2) + 16 * ((IT) & 3); _Pragma("unroll") for (int bj = 0; bj < 2; ++bj) \
;             xin[BUF][bj] = *(const u32x4*)(XG + (row_ * DM + cbase + bj * 128)); } while (0)
;     __device__ __forceinline__ void operator()(f32x4 (&acc)[2][2][4][2], const Unit& u, int ui, int wr, int wc, int fr, int fq, int lane, LAS unsigned char* lds) const {
;     ...
;         EPR_LOAD(0, 0);
; #pragma unroll
;         for (int it = 0; it < 8; ++it) {
;             if (it + 1 < 8) EPR_LOAD(it + 1, (it + 1) & 1);
;             __builtin_amdgcn_sched_barrier(0);
;             const int ai = it >> 2, m = it & 3;
;             const unsigned row = rb + 128 * ai + 16 * m;
;             float ss = 0.f;
; #pragma unroll
;             for (int bj = 0; bj < 2; ++bj) {
;                 const u32x4 xw = xin[it & 1][bj];
;                 f32x4 v0, v1;
;                 v0[0] = __builtin_bit_cast(float, xw.x << 16); v0[1] = __builtin_bit_cast(float, xw.x & 0xffff0000u); v0[2] = __builtin_bit_cast(float, xw.y << 16); v0[3] = __builtin_bit_cast(float, xw.y & 0xffff0000u);
;                 v1[0] = __builtin_bit_cast(float, xw.z << 16); v1[1] = __builtin_bit_cast(float, xw.z & 0xffff0000u); v1[2] = __builtin_bit_cast(float, xw.w << 16); v1[3] = __builtin_bit_cast(float, xw.w & 0xffff0000u);
;                 v0 += acc[ai][bj][m][0]; v1 += acc[ai][bj][m][1];
;                 ss += ((v0[0] * v0[0] + v0[1] * v0[1]) + (v0[2] * v0[2] + v0[3] * v0[3])) + ((v1[0] * v1[0] + v1[1] * v1[1]) + (v1[2] * v1[2] + v1[3] * v1[3]));
;                 u32x4 w; w.x = cvt_pk_bf16(v0[0], v0[1]); w.y = cvt_pk_bf16(v0[2], v0[3]); w.z = cvt_pk_bf16(v1[0], v1[1]); w.w = cvt_pk_bf16(v1[2], v1[3]);
;                 *(u32x4*)(XG + (row * DM + cbase + bj * 128)) = w;
;             }
;             ss += __shfl_xor(ss, 16); ss += __shfl_xor(ss, 32);
;             if (fq == 0) red[(128 * ai + 64 * wr + 16 * m + fr) * 4 + wc] = ss;
.LBB0_652:
	s_or_b64 exec, exec, s[4:5]
	v_add_u32_e32 v80, 0x20000, v188
	s_waitcnt lgkmcnt(0)
	v_mov_b32_e32 v81, v189
	v_lshl_add_u64 v[90:91], v[80:81], 1, s[8:9]
	v_add_u32_e32 v80, 0x20080, v188
	v_lshl_add_u64 v[88:89], v[80:81], 1, s[8:9]
	s_waitcnt vmcnt(15)
	v_lshlrev_b32_e32 v92, 16, v170
	v_and_b32_e32 v93, 0xffff0000, v170
	v_lshlrev_b32_e32 v94, 16, v171
	v_and_b32_e32 v95, 0xffff0000, v171
	v_lshlrev_b32_e32 v100, 16, v172
	v_and_b32_e32 v101, 0xffff0000, v172
	v_lshlrev_b32_e32 v102, 16, v173
	v_and_b32_e32 v103, 0xffff0000, v173
	v_pk_add_f32 v[78:79], v[78:79], v[94:95]
	v_pk_add_f32 v[76:77], v[76:77], v[92:93]
	v_pk_add_f32 v[92:93], v[74:75], v[102:103]
	v_pk_add_f32 v[74:75], v[72:73], v[100:101]
	v_mul_f32_e32 v72, v77, v77
	v_mul_f32_e32 v73, v79, v79
	v_fmac_f32_e32 v72, v76, v76
	v_fmac_f32_e32 v73, v78, v78
	v_add_f32_e32 v72, v72, v73
	v_mul_f32_e32 v73, v75, v75
	v_mul_f32_e32 v94, v93, v93
	v_fmac_f32_e32 v73, v74, v74
	v_fmac_f32_e32 v94, v92, v92
	v_add_f32_e32 v73, v73, v94
	v_add_f32_e32 v100, v72, v73
	v_cvt_pk_bf16_f32 v72, v76, v77
	v_cvt_pk_bf16_f32 v73, v78, v79
	s_waitcnt vmcnt(14)
	v_lshlrev_b32_e32 v76, 16, v174
	v_and_b32_e32 v77, 0xffff0000, v174
	v_lshlrev_b32_e32 v78, 16, v175
	v_and_b32_e32 v79, 0xffff0000, v175
	v_lshlrev_b32_e32 v94, 16, v176
	v_and_b32_e32 v95, 0xffff0000, v176
	v_pk_add_f32 v[70:71], v[70:71], v[78:79]
	v_pk_add_f32 v[68:69], v[68:69], v[76:77]
	v_lshlrev_b32_e32 v96, 16, v177
	v_and_b32_e32 v97, 0xffff0000, v177
	v_pk_add_f32 v[78:79], v[64:65], v[94:95]
	v_mul_f32_e32 v64, v69, v69
	v_mul_f32_e32 v65, v71, v71
	v_pk_add_f32 v[76:77], v[66:67], v[96:97]
	v_fmac_f32_e32 v64, v68, v68
	v_fmac_f32_e32 v65, v70, v70
	v_add_f32_e32 v64, v64, v65
	v_mul_f32_e32 v65, v79, v79
	v_mul_f32_e32 v66, v77, v77
	v_fmac_f32_e32 v65, v78, v78
	v_fmac_f32_e32 v66, v76, v76
	v_add_f32_e32 v65, v65, v66
	v_add_f32_e32 v64, v64, v65
	v_add_f32_e32 v64, v100, v64
	v_mov_b32_e32 v65, v64
	s_nop 1
	v_permlane16_swap_b32 v65, v64
	v_cvt_pk_bf16_f32 v74, v74, v75
	v_cvt_pk_bf16_f32 v75, v92, v93
	global_store_dwordx4 v[106:107], v[72:75], off
	v_cvt_pk_bf16_f32 v66, v68, v69
	s_waitcnt lgkmcnt(0)
	v_add_f32_e32 v64, v64, v65
	v_mov_b32_e32 v65, v64
	s_nop 1
	v_permlane32_swap_b32 v65, v64
	v_cvt_pk_bf16_f32 v67, v70, v71
	v_cvt_pk_bf16_f32 v68, v78, v79
	v_cvt_pk_bf16_f32 v69, v76, v77
	global_store_dwordx4 v[104:105], v[66:69], off
	s_and_saveexec_b64 s[4:5], vcc
	s_cbranch_execz .LBB0_654
	s_waitcnt lgkmcnt(0)
	v_add_f32_e32 v64, v64, v65
	ds_write_b32 v124, v64 offset:768
.LBB0_654:
	s_or_b64 exec, exec, s[4:5]
	v_add_u32_e32 v64, 0x24000, v188
	s_waitcnt lgkmcnt(0)
	v_mov_b32_e32 v65, v189
	v_lshl_add_u64 v[74:75], v[64:65], 1, s[8:9]
	v_add_u32_e32 v64, 0x24080, v188
	v_lshl_add_u64 v[72:73], v[64:65], 1, s[8:9]
	s_waitcnt vmcnt(15)
	v_lshlrev_b32_e32 v76, 16, v178
	v_and_b32_e32 v77, 0xffff0000, v178
	v_lshlrev_b32_e32 v78, 16, v179
	v_and_b32_e32 v79, 0xffff0000, v179
	v_lshlrev_b32_e32 v84, 16, v180
	v_and_b32_e32 v85, 0xffff0000, v180
	v_lshlrev_b32_e32 v86, 16, v181
	v_and_b32_e32 v87, 0xffff0000, v181
	v_pk_add_f32 v[62:63], v[62:63], v[78:79]
	v_pk_add_f32 v[60:61], v[60:61], v[76:77]
	v_pk_add_f32 v[76:77], v[58:59], v[86:87]
	v_pk_add_f32 v[58:59], v[56:57], v[84:85]
	v_mul_f32_e32 v56, v61, v61
	v_mul_f32_e32 v57, v63, v63
	v_fmac_f32_e32 v56, v60, v60
	v_fmac_f32_e32 v57, v62, v62
	v_add_f32_e32 v56, v56, v57
	v_mul_f32_e32 v57, v59, v59
	v_mul_f32_e32 v78, v77, v77
	v_fmac_f32_e32 v57, v58, v58
	v_fmac_f32_e32 v78, v76, v76
	v_add_f32_e32 v57, v57, v78
	v_add_f32_e32 v84, v56, v57
	v_cvt_pk_bf16_f32 v56, v60, v61
	v_cvt_pk_bf16_f32 v57, v62, v63
	s_waitcnt vmcnt(14)
	v_lshlrev_b32_e32 v60, 16, v182
	v_and_b32_e32 v61, 0xffff0000, v182
	v_lshlrev_b32_e32 v62, 16, v183
	v_and_b32_e32 v63, 0xffff0000, v183
	v_lshlrev_b32_e32 v78, 16, v184
	v_and_b32_e32 v79, 0xffff0000, v184
	v_pk_add_f32 v[54:55], v[54:55], v[62:63]
	v_pk_add_f32 v[52:53], v[52:53], v[60:61]
	v_lshlrev_b32_e32 v80, 16, v185
	v_and_b32_e32 v81, 0xffff0000, v185
	v_pk_add_f32 v[62:63], v[48:49], v[78:79]
	v_mul_f32_e32 v48, v53, v53
	v_mul_f32_e32 v49, v55, v55
	v_pk_add_f32 v[60:61], v[50:51], v[80:81]
	v_fmac_f32_e32 v48, v52, v52
	v_fmac_f32_e32 v49, v54, v54
	v_add_f32_e32 v48, v48, v49
	v_mul_f32_e32 v49, v63, v63
	v_mul_f32_e32 v50, v61, v61
	v_fmac_f32_e32 v49, v62, v62
	v_fmac_f32_e32 v50, v60, v60
	v_add_f32_e32 v49, v49, v50
	v_add_f32_e32 v48, v48, v49
	v_add_f32_e32 v48, v84, v48
	v_mov_b32_e32 v49, v48
	s_nop 1
	v_permlane16_swap_b32 v49, v48
	v_cvt_pk_bf16_f32 v58, v58, v59
	v_cvt_pk_bf16_f32 v59, v76, v77
	global_store_dwordx4 v[90:91], v[56:59], off
	v_cvt_pk_bf16_f32 v50, v52, v53
	s_waitcnt lgkmcnt(0)
	v_add_f32_e32 v48, v48, v49
	v_mov_b32_e32 v49, v48
	s_nop 1
	v_permlane32_swap_b32 v49, v48
	v_cvt_pk_bf16_f32 v51, v54, v55
	v_cvt_pk_bf16_f32 v52, v62, v63
	v_cvt_pk_bf16_f32 v53, v60, v61
	global_store_dwordx4 v[88:89], v[50:53], off
	s_and_saveexec_b64 s[4:5], vcc
	s_cbranch_execz .LBB0_656
	s_waitcnt lgkmcnt(0)
	v_add_f32_e32 v48, v48, v49
	ds_write_b32 v124, v48 offset:2048
; __device__ __forceinline__ unsigned cvt_pk_bf16(float lo, float hi) { unsigned r; asm volatile("v_cvt_pk_bf16_f32 %0, %1, %2" : "=v"(r) : "v"(lo), "v"(hi)); return r; }
; #define EPR_LOAD(IT, BUF) do { const unsigned row_ = rb + 128 * ((IT) >> 2) + 16 * ((IT) & 3); _Pragma("unroll") for (int bj = 0; bj < 2; ++bj) \
;             xin[BUF][bj] = *(const u32x4*)(XG + (row_ * DM + cbase + bj * 128)); } while (0)
;     __device__ __forceinline__ void operator()(f32x4 (&acc)[2][2][4][2], const Unit& u, int ui, int wr, int wc, int fr, int fq, int lane, LAS unsigned char* lds) const {
;     ...
;         EPR_LOAD(0, 0);
; #pragma unroll
;         for (int it = 0; it < 8; ++it) {
;             if (it + 1 < 8) EPR_LOAD(it + 1, (it + 1) & 1);
;             __builtin_amdgcn_sched_barrier(0);
;             const int ai = it >> 2, m = it & 3;
;             const unsigned row = rb + 128 * ai + 16 * m;
;             float ss = 0.f;
; #pragma unroll
;             for (int bj = 0; bj < 2; ++bj) {
;                 const u32x4 xw = xin[it & 1][bj];
;                 f32x4 v0, v1;
;                 v0[0] = __builtin_bit_cast(float, xw.x << 16); v0[1] = __builtin_bit_cast(float, xw.x & 0xffff0000u); v0[2] = __builtin_bit_cast(float, xw.y << 16); v0[3] = __builtin_bit_cast(float, xw.y & 0xffff0000u);
;                 v1[0] = __builtin_bit_cast(float, xw.z << 16); v1[1] = __builtin_bit_cast(float, xw.z & 0xffff0000u); v1[2] = __builtin_bit_cast(float, xw.w << 16); v1[3] = __builtin_bit_cast(float, xw.w & 0xffff0000u);
;                 v0 += acc[ai][bj][m][0]; v1 += acc[ai][bj][m][1];
;                 ss += ((v0[0] * v0[0] + v0[1] * v0[1]) + (v0[2] * v0[2] + v0[3] * v0[3])) + ((v1[0] * v1[0] + v1[1] * v1[1]) + (v1[2] * v1[2] + v1[3] * v1[3]));
;                 u32x4 w; w.x = cvt_pk_bf16(v0[0], v0[1]); w.y = cvt_pk_bf16(v0[2], v0[3]); w.z = cvt_pk_bf16(v1[0], v1[1]); w.w = cvt_pk_bf16(v1[2], v1[3]);
;                 *(u32x4*)(XG + (row * DM + cbase + bj * 128)) = w;
;             }
;             ss += __shfl_xor(ss, 16); ss += __shfl_xor(ss, 32);
;             if (fq == 0) red[(128 * ai + 64 * wr + 16 * m + fr) * 4 + wc] = ss;
.LBB0_656:
	s_or_b64 exec, exec, s[4:5]
	v_add_u32_e32 v48, 0x28000, v188
	s_waitcnt lgkmcnt(0)
	v_mov_b32_e32 v49, v189
	v_lshl_add_u64 v[58:59], v[48:49], 1, s[8:9]
	v_add_u32_e32 v48, 0x28080, v188
	v_lshl_add_u64 v[56:57], v[48:49], 1, s[8:9]
	s_waitcnt vmcnt(15)
	v_lshlrev_b32_e32 v60, 16, v194
	v_and_b32_e32 v61, 0xffff0000, v194
	v_lshlrev_b32_e32 v62, 16, v195
	v_and_b32_e32 v63, 0xffff0000, v195
	v_lshlrev_b32_e32 v68, 16, v196
	v_and_b32_e32 v69, 0xffff0000, v196
	v_lshlrev_b32_e32 v70, 16, v197
	v_and_b32_e32 v71, 0xffff0000, v197
	v_pk_add_f32 v[46:47], v[46:47], v[62:63]
	v_pk_add_f32 v[44:45], v[44:45], v[60:61]
	v_pk_add_f32 v[60:61], v[42:43], v[70:71]
	v_pk_add_f32 v[42:43], v[40:41], v[68:69]
	v_mul_f32_e32 v40, v45, v45
	v_mul_f32_e32 v41, v47, v47
	v_fmac_f32_e32 v40, v44, v44
	v_fmac_f32_e32 v41, v46, v46
	v_add_f32_e32 v40, v40, v41
	v_mul_f32_e32 v41, v43, v43
	v_mul_f32_e32 v62, v61, v61
	v_fmac_f32_e32 v41, v42, v42
	v_fmac_f32_e32 v62, v60, v60
	v_add_f32_e32 v41, v41, v62
	v_add_f32_e32 v68, v40, v41
	v_cvt_pk_bf16_f32 v40, v44, v45
	v_cvt_pk_bf16_f32 v41, v46, v47
	s_waitcnt vmcnt(14)
	v_lshlrev_b32_e32 v44, 16, v198
	v_and_b32_e32 v45, 0xffff0000, v198
	v_lshlrev_b32_e32 v46, 16, v199
	v_and_b32_e32 v47, 0xffff0000, v199
	v_lshlrev_b32_e32 v62, 16, v200
	v_and_b32_e32 v63, 0xffff0000, v200
	v_pk_add_f32 v[38:39], v[38:39], v[46:47]
	v_pk_add_f32 v[36:37], v[36:37], v[44:45]
	v_lshlrev_b32_e32 v64, 16, v201
	v_and_b32_e32 v65, 0xffff0000, v201
	v_pk_add_f32 v[46:47], v[32:33], v[62:63]
	v_mul_f32_e32 v32, v37, v37
	v_mul_f32_e32 v33, v39, v39
	v_pk_add_f32 v[44:45], v[34:35], v[64:65]
	v_fmac_f32_e32 v32, v36, v36
	v_fmac_f32_e32 v33, v38, v38
	v_add_f32_e32 v32, v32, v33
	v_mul_f32_e32 v33, v47, v47
	v_mul_f32_e32 v34, v45, v45
	v_fmac_f32_e32 v33, v46, v46
	v_fmac_f32_e32 v34, v44, v44
	v_add_f32_e32 v33, v33, v34
	v_add_f32_e32 v32, v32, v33
	v_add_f32_e32 v32, v68, v32
	v_mov_b32_e32 v33, v32
	s_nop 1
	v_permlane16_swap_b32 v33, v32
	v_cvt_pk_bf16_f32 v42, v42, v43
	v_cvt_pk_bf16_f32 v43, v60, v61
	global_store_dwordx4 v[74:75], v[40:43], off
	v_cvt_pk_bf16_f32 v34, v36, v37
	s_waitcnt lgkmcnt(0)
	v_add_f32_e32 v32, v32, v33
	v_mov_b32_e32 v33, v32
	s_nop 1
	v_permlane32_swap_b32 v33, v32
	v_cvt_pk_bf16_f32 v35, v38, v39
	v_cvt_pk_bf16_f32 v36, v46, v47
	v_cvt_pk_bf16_f32 v37, v44, v45
	global_store_dwordx4 v[72:73], v[34:37], off
	s_and_saveexec_b64 s[4:5], vcc
	s_cbranch_execz .LBB0_658
	s_waitcnt lgkmcnt(0)
	v_add_f32_e32 v32, v32, v33
	ds_write_b32 v124, v32 offset:2304
; __device__ __forceinline__ unsigned cvt_pk_bf16(float lo, float hi) { unsigned r; asm volatile("v_cvt_pk_bf16_f32 %0, %1, %2" : "=v"(r) : "v"(lo), "v"(hi)); return r; }
; #define EPR_LOAD(IT, BUF) do { const unsigned row_ = rb + 128 * ((IT) >> 2) + 16 * ((IT) & 3); _Pragma("unroll") for (int bj = 0; bj < 2; ++bj) \
;             xin[BUF][bj] = *(const u32x4*)(XG + (row_ * DM + cbase + bj * 128)); } while (0)
;     __device__ __forceinline__ void operator()(f32x4 (&acc)[2][2][4][2], const Unit& u, int ui, int wr, int wc, int fr, int fq, int lane, LAS unsigned char* lds) const {
;     ...
;         EPR_LOAD(0, 0);
; #pragma unroll
;         for (int it = 0; it < 8; ++it) {
;             if (it + 1 < 8) EPR_LOAD(it + 1, (it + 1) & 1);
;             __builtin_amdgcn_sched_barrier(0);
;             const int ai = it >> 2, m = it & 3;
;             const unsigned row = rb + 128 * ai + 16 * m;
;             float ss = 0.f;
; #pragma unroll
;             for (int bj = 0; bj < 2; ++bj) {
;                 const u32x4 xw = xin[it & 1][bj];
;                 f32x4 v0, v1;
;                 v0[0] = __builtin_bit_cast(float, xw.x << 16); v0[1] = __builtin_bit_cast(float, xw.x & 0xffff0000u); v0[2] = __builtin_bit_cast(float, xw.y << 16); v0[3] = __builtin_bit_cast(float, xw.y & 0xffff0000u);
;                 v1[0] = __builtin_bit_cast(float, xw.z << 16); v1[1] = __builtin_bit_cast(float, xw.z & 0xffff0000u); v1[2] = __builtin_bit_cast(float, xw.w << 16); v1[3] = __builtin_bit_cast(float, xw.w & 0xffff0000u);
;                 v0 += acc[ai][bj][m][0]; v1 += acc[ai][bj][m][1];
;                 ss += ((v0[0] * v0[0] + v0[1] * v0[1]) + (v0[2] * v0[2] + v0[3] * v0[3])) + ((v1[0] * v1[0] + v1[1] * v1[1]) + (v1[2] * v1[2] + v1[3] * v1[3]));
;                 u32x4 w; w.x = cvt_pk_bf16(v0[0], v0[1]); w.y = cvt_pk_bf16(v0[2], v0[3]); w.z = cvt_pk_bf16(v1[0], v1[1]); w.w = cvt_pk_bf16(v1[2], v1[3]);
;                 *(u32x4*)(XG + (row * DM + cbase + bj * 128)) = w;
;             }
;             ss += __shfl_xor(ss, 16); ss += __shfl_xor(ss, 32);
;             if (fq == 0) red[(128 * ai + 64 * wr + 16 * m + fr) * 4 + wc] = ss;
.LBB0_658:
	s_or_b64 exec, exec, s[4:5]
	v_add_u32_e32 v32, 0x2c000, v188
	s_waitcnt lgkmcnt(0)
	v_mov_b32_e32 v33, v189
	v_lshl_add_u64 v[42:43], v[32:33], 1, s[8:9]
	v_add_u32_e32 v188, 0x2c080, v188
	v_lshl_add_u64 v[40:41], v[188:189], 1, s[8:9]
	s_waitcnt vmcnt(15)
	v_lshlrev_b32_e32 v44, 16, v202
	v_and_b32_e32 v45, 0xffff0000, v202
	v_lshlrev_b32_e32 v46, 16, v203
	v_and_b32_e32 v47, 0xffff0000, v203
	v_lshlrev_b32_e32 v52, 16, v204
	v_and_b32_e32 v53, 0xffff0000, v204
	v_lshlrev_b32_e32 v54, 16, v205
	v_and_b32_e32 v55, 0xffff0000, v205
	v_pk_add_f32 v[30:31], v[30:31], v[46:47]
	v_pk_add_f32 v[28:29], v[28:29], v[44:45]
	v_pk_add_f32 v[44:45], v[26:27], v[54:55]
	v_pk_add_f32 v[26:27], v[24:25], v[52:53]
	v_mul_f32_e32 v24, v29, v29
	v_mul_f32_e32 v25, v31, v31
	v_fmac_f32_e32 v24, v28, v28
	v_fmac_f32_e32 v25, v30, v30
	v_add_f32_e32 v24, v24, v25
	v_mul_f32_e32 v25, v27, v27
	v_mul_f32_e32 v46, v45, v45
	v_fmac_f32_e32 v25, v26, v26
	v_fmac_f32_e32 v46, v44, v44
	v_add_f32_e32 v25, v25, v46
	v_add_f32_e32 v52, v24, v25
	v_cvt_pk_bf16_f32 v24, v28, v29
	v_cvt_pk_bf16_f32 v25, v30, v31
	s_waitcnt vmcnt(14)
	v_lshlrev_b32_e32 v28, 16, v212
	v_and_b32_e32 v29, 0xffff0000, v212
	v_lshlrev_b32_e32 v30, 16, v213
	v_and_b32_e32 v31, 0xffff0000, v213
	v_lshlrev_b32_e32 v46, 16, v214
	v_and_b32_e32 v47, 0xffff0000, v214
	v_pk_add_f32 v[22:23], v[22:23], v[30:31]
	v_pk_add_f32 v[20:21], v[20:21], v[28:29]
	v_lshlrev_b32_e32 v48, 16, v215
	v_and_b32_e32 v49, 0xffff0000, v215
	v_pk_add_f32 v[30:31], v[16:17], v[46:47]
	v_mul_f32_e32 v16, v21, v21
	v_mul_f32_e32 v17, v23, v23
	v_pk_add_f32 v[28:29], v[18:19], v[48:49]
	v_fmac_f32_e32 v16, v20, v20
	v_fmac_f32_e32 v17, v22, v22
	v_add_f32_e32 v16, v16, v17
	v_mul_f32_e32 v17, v31, v31
	v_mul_f32_e32 v18, v29, v29
	v_fmac_f32_e32 v17, v30, v30
	v_fmac_f32_e32 v18, v28, v28
	v_add_f32_e32 v17, v17, v18
	v_add_f32_e32 v16, v16, v17
	v_add_f32_e32 v16, v52, v16
	v_mov_b32_e32 v17, v16
	s_nop 1
	v_permlane16_swap_b32 v17, v16
	v_cvt_pk_bf16_f32 v26, v26, v27
	v_cvt_pk_bf16_f32 v27, v44, v45
	global_store_dwordx4 v[58:59], v[24:27], off
	v_cvt_pk_bf16_f32 v18, v20, v21
	s_waitcnt lgkmcnt(0)
	v_add_f32_e32 v16, v16, v17
	v_mov_b32_e32 v17, v16
	s_nop 1
	v_permlane32_swap_b32 v17, v16
	v_cvt_pk_bf16_f32 v19, v22, v23
	v_cvt_pk_bf16_f32 v20, v30, v31
	v_cvt_pk_bf16_f32 v21, v28, v29
	global_store_dwordx4 v[56:57], v[18:21], off
	s_and_saveexec_b64 s[4:5], vcc
	s_cbranch_execz .LBB0_660
	s_waitcnt lgkmcnt(0)
	v_add_f32_e32 v16, v16, v17
	ds_write_b32 v124, v16 offset:2560
.LBB0_660:
	s_or_b64 exec, exec, s[4:5]
	s_waitcnt vmcnt(15)
	v_lshlrev_b32_e32 v16, 16, v216
	s_waitcnt lgkmcnt(0)
	v_and_b32_e32 v17, 0xffff0000, v216
	v_lshlrev_b32_e32 v18, 16, v217
	v_and_b32_e32 v19, 0xffff0000, v217
	v_lshlrev_b32_e32 v20, 16, v218
	v_and_b32_e32 v21, 0xffff0000, v218
	v_lshlrev_b32_e32 v22, 16, v219
	v_and_b32_e32 v23, 0xffff0000, v219
	v_pk_add_f32 v[14:15], v[14:15], v[18:19]
	v_pk_add_f32 v[12:13], v[12:13], v[16:17]
	v_pk_add_f32 v[16:17], v[10:11], v[22:23]
	v_pk_add_f32 v[10:11], v[8:9], v[20:21]
	v_mul_f32_e32 v8, v13, v13
	v_mul_f32_e32 v9, v15, v15
	v_fmac_f32_e32 v8, v12, v12
	v_fmac_f32_e32 v9, v14, v14
	v_add_f32_e32 v8, v8, v9
	v_mul_f32_e32 v9, v11, v11
	v_mul_f32_e32 v18, v17, v17
	v_fmac_f32_e32 v9, v10, v10
	v_fmac_f32_e32 v18, v16, v16
	v_add_f32_e32 v9, v9, v18
	v_add_f32_e32 v22, v8, v9
	v_cvt_pk_bf16_f32 v8, v12, v13
	v_cvt_pk_bf16_f32 v9, v14, v15
	s_waitcnt vmcnt(14)
	v_lshlrev_b32_e32 v12, 16, v220
	v_and_b32_e32 v13, 0xffff0000, v220
	v_lshlrev_b32_e32 v14, 16, v221
	v_and_b32_e32 v15, 0xffff0000, v221
	v_lshlrev_b32_e32 v18, 16, v222
	v_and_b32_e32 v19, 0xffff0000, v222
	v_pk_add_f32 v[6:7], v[6:7], v[14:15]
	v_pk_add_f32 v[4:5], v[4:5], v[12:13]
	v_lshlrev_b32_e32 v20, 16, v223
	v_and_b32_e32 v21, 0xffff0000, v223
	v_pk_add_f32 v[14:15], v[0:1], v[18:19]
	v_mul_f32_e32 v0, v5, v5
	v_mul_f32_e32 v1, v7, v7
	v_pk_add_f32 v[12:13], v[2:3], v[20:21]
	v_fmac_f32_e32 v0, v4, v4
	v_fmac_f32_e32 v1, v6, v6
	v_add_f32_e32 v0, v0, v1
	v_mul_f32_e32 v1, v15, v15
	v_mul_f32_e32 v2, v13, v13
	v_fmac_f32_e32 v1, v14, v14
	v_fmac_f32_e32 v2, v12, v12
	v_add_f32_e32 v1, v1, v2
	v_add_f32_e32 v0, v0, v1
	v_add_f32_e32 v0, v22, v0
	v_mov_b32_e32 v1, v0
	s_nop 1
	v_permlane16_swap_b32 v1, v0
	v_cvt_pk_bf16_f32 v10, v10, v11
	v_cvt_pk_bf16_f32 v11, v16, v17
	global_store_dwordx4 v[42:43], v[8:11], off
	v_cvt_pk_bf16_f32 v2, v4, v5
	s_waitcnt lgkmcnt(0)
	v_add_f32_e32 v0, v0, v1
	v_mov_b32_e32 v1, v0
	s_nop 1
	v_permlane32_swap_b32 v1, v0
	v_cvt_pk_bf16_f32 v3, v6, v7
	v_cvt_pk_bf16_f32 v4, v14, v15
	v_cvt_pk_bf16_f32 v5, v12, v13
	global_store_dwordx4 v[40:41], v[2:5], off
	s_and_saveexec_b64 s[4:5], vcc
	s_cbranch_execz .LBB0_662
	s_waitcnt lgkmcnt(0)
	v_add_f32_e32 v0, v0, v1
	ds_write_b32 v124, v0 offset:2816

; __device__ __forceinline__ unsigned cvt_pk_bf16(float lo, float hi) { unsigned r; asm volatile("v_cvt_pk_bf16_f32 %0, %1, %2" : "=v"(r) : "v"(lo), "v"(hi)); return r; }
; #define EPR_LOAD(IT, BUF) do { const unsigned row_ = rb + 128 * ((IT) >> 2) + 16 * ((IT) & 3); _Pragma("unroll") for (int bj = 0; bj < 2; ++bj) \
;             xin[BUF][bj] = *(const u32x4*)(XG + (row_ * DM + cbase + bj * 128)); } while (0)
;     __device__ __forceinline__ void operator()(f32x4 (&acc)[2][2][4][2], const Unit& u, int ui, int wr, int wc, int fr, int fq, int lane, LAS unsigned char* lds) const {
;     ...
;         EPR_LOAD(0, 0);
; #pragma unroll
;         for (int it = 0; it < 8; ++it) {
;             if (it + 1 < 8) EPR_LOAD(it + 1, (it + 1) & 1);
;             __builtin_amdgcn_sched_barrier(0);
;             const int ai = it >> 2, m = it & 3;
;             const unsigned row = rb + 128 * ai + 16 * m;
;             float ss = 0.f;
; #pragma unroll
;             for (int bj = 0; bj < 2; ++bj) {
;                 const u32x4 xw = xin[it & 1][bj];
;                 f32x4 v0, v1;
;                 v0[0] = __builtin_bit_cast(float, xw.x << 16); v0[1] = __builtin_bit_cast(float, xw.x & 0xffff0000u); v0[2] = __builtin_bit_cast(float, xw.y << 16); v0[3] = __builtin_bit_cast(float, xw.y & 0xffff0000u);
;                 v1[0] = __builtin_bit_cast(float, xw.z << 16); v1[1] = __builtin_bit_cast(float, xw.z & 0xffff0000u); v1[2] = __builtin_bit_cast(float, xw.w << 16); v1[3] = __builtin_bit_cast(float, xw.w & 0xffff0000u);
;                 v0 += acc[ai][bj][m][0]; v1 += acc[ai][bj][m][1];
;                 ss += ((v0[0] * v0[0] + v0[1] * v0[1]) + (v0[2] * v0[2] + v0[3] * v0[3])) + ((v1[0] * v1[0] + v1[1] * v1[1]) + (v1[2] * v1[2] + v1[3] * v1[3]));
;                 u32x4 w; w.x = cvt_pk_bf16(v0[0], v0[1]); w.y = cvt_pk_bf16(v0[2], v0[3]); w.z = cvt_pk_bf16(v1[0], v1[1]); w.w = cvt_pk_bf16(v1[2], v1[3]);
;                 *(u32x4*)(XG + (row * DM + cbase + bj * 128)) = w;
;             }
;             ss += __shfl_xor(ss, 16); ss += __shfl_xor(ss, 32);
;             if (fq == 0) red[(128 * ai + 64 * wr + 16 * m + fr) * 4 + wc] = ss;
.LBB0_991:
	s_and_b64 vcc, exec, s[26:27]
	s_cbranch_vccz .LBB0_1011
	v_mov_b32_e32 v128, v145
	v_mov_b32_e32 v148, v146
	v_mov_b32_e32 v130, v147
	s_lshl_b32 s0, s43, 8
	s_lshl_b32 s1, s44, 18
	v_add_u32_e32 v149, s55, v128
	s_or_b32 s0, s0, s57
	v_lshlrev_b32_e32 v129, 3, v130
	v_lshlrev_b32_e32 v128, 10, v149
	s_add_i32 s0, s0, s1
	v_add3_u32 v138, s0, v129, v128
	v_add_u32_e32 v128, 0x80, v138
	v_mov_b32_e32 v129, v189
	v_lshl_add_u64 v[160:161], v[128:129], 1, s[10:11]
	v_add_u32_e32 v128, 0x4000, v138
	v_lshl_add_u64 v[140:141], v[128:129], 1, s[10:11]
	v_add_u32_e32 v128, 0x4080, v138
	v_mov_b32_e32 v139, v189
	v_lshl_add_u64 v[142:143], v[128:129], 1, s[10:11]
	v_lshl_add_u64 v[158:159], v[138:139], 1, s[10:11]
	v_cmp_eq_u32_e32 vcc, 0, v130
	global_load_dwordx4 v[132:135], v[140:141], off
	global_load_dwordx4 v[128:131], v[142:143], off
	global_load_dwordx4 v[150:153], v[158:159], off
	global_load_dwordx4 v[154:157], v[160:161], off
	s_mov_b32 s99, 0
	s_mov_b32 s98, 0x10000
	v_lshl_add_u64 v[186:187], v[158:159], 0, s[98:99]
	global_load_dwordx4 v[166:169], v[186:187], off
	global_load_dwordx4 v[170:173], v[186:187], off offset:256
	s_mov_b32 s98, 0x18000
	v_lshl_add_u64 v[186:187], v[158:159], 0, s[98:99]
	global_load_dwordx4 v[174:177], v[186:187], off
	global_load_dwordx4 v[178:181], v[186:187], off offset:256
	s_mov_b32 s98, 0x40000
	v_lshl_add_u64 v[186:187], v[158:159], 0, s[98:99]
	global_load_dwordx4 v[182:185], v[186:187], off
	global_load_dwordx4 v[194:197], v[186:187], off offset:256
	s_mov_b32 s98, 0x48000
	v_lshl_add_u64 v[186:187], v[158:159], 0, s[98:99]
	global_load_dwordx4 v[198:201], v[186:187], off
	global_load_dwordx4 v[202:205], v[186:187], off offset:256
	s_mov_b32 s98, 0x50000
	v_lshl_add_u64 v[186:187], v[158:159], 0, s[98:99]
	global_load_dwordx4 v[212:215], v[186:187], off
	global_load_dwordx4 v[216:219], v[186:187], off offset:256
	s_mov_b32 s98, 0x58000
	v_lshl_add_u64 v[186:187], v[158:159], 0, s[98:99]
	global_load_dwordx4 v[220:223], v[186:187], off
	global_load_dwordx4 v[224:227], v[186:187], off offset:256
	s_waitcnt vmcnt(12)
	v_lshlrev_b32_e32 v162, 16, v150
	v_and_b32_e32 v163, 0xffff0000, v150
	v_lshlrev_b32_e32 v150, 16, v151
	v_and_b32_e32 v151, 0xffff0000, v151
	v_lshlrev_b32_e32 v164, 16, v152
	v_and_b32_e32 v165, 0xffff0000, v152
	v_lshlrev_b32_e32 v152, 16, v153
	v_and_b32_e32 v153, 0xffff0000, v153
	v_pk_add_f32 v[126:127], v[126:127], v[150:151]
	v_pk_add_f32 v[124:125], v[124:125], v[162:163]
	v_pk_add_f32 v[150:151], v[122:123], v[152:153]
	v_pk_add_f32 v[122:123], v[120:121], v[164:165]
	v_mul_f32_e32 v120, v125, v125
	v_mul_f32_e32 v121, v127, v127
	v_fmac_f32_e32 v120, v124, v124
	v_fmac_f32_e32 v121, v126, v126
	v_add_f32_e32 v120, v120, v121
	v_mul_f32_e32 v121, v123, v123
	v_mul_f32_e32 v139, v151, v151
	v_fmac_f32_e32 v121, v122, v122
	v_fmac_f32_e32 v139, v150, v150
	v_add_f32_e32 v121, v121, v139
	v_add_f32_e32 v139, v120, v121
	v_cvt_pk_bf16_f32 v120, v124, v125
	v_cvt_pk_bf16_f32 v121, v126, v127
	v_lshlrev_b32_e32 v124, 16, v154
	v_and_b32_e32 v125, 0xffff0000, v154
	v_lshlrev_b32_e32 v126, 16, v155
	v_and_b32_e32 v127, 0xffff0000, v155
	v_lshlrev_b32_e32 v152, 16, v156
	v_and_b32_e32 v153, 0xffff0000, v156
	v_pk_add_f32 v[118:119], v[118:119], v[126:127]
	v_pk_add_f32 v[116:117], v[116:117], v[124:125]
	v_lshlrev_b32_e32 v154, 16, v157
	v_and_b32_e32 v155, 0xffff0000, v157
	v_pk_add_f32 v[152:153], v[112:113], v[152:153]
	v_mul_f32_e32 v112, v117, v117
	v_mul_f32_e32 v113, v119, v119
	v_pk_add_f32 v[154:155], v[114:115], v[154:155]
	v_fmac_f32_e32 v112, v116, v116
	v_fmac_f32_e32 v113, v118, v118
	v_add_f32_e32 v112, v112, v113
	v_mul_f32_e32 v113, v153, v153
	v_mul_f32_e32 v114, v155, v155
	v_fmac_f32_e32 v113, v152, v152
	v_fmac_f32_e32 v114, v154, v154
	v_add_f32_e32 v113, v113, v114
	v_and_b32_e32 v114, 64, v208
	v_add_f32_e32 v112, v112, v113
	v_xor_b32_e32 v113, 16, v208
	v_add_u32_e32 v124, 64, v114
	v_cmp_lt_i32_e64 s[6:7], v113, v124
	v_add_f32_e32 v112, v139, v112
	v_cvt_pk_bf16_f32 v122, v122, v123
	v_cvt_pk_bf16_f32 v123, v150, v151
	global_store_dwordx4 v[158:159], v[120:123], off
	v_cndmask_b32_e64 v113, v208, v113, s[6:7]
	v_lshlrev_b32_e32 v125, 2, v113
	v_mov_b32_e32 v113, v112
	s_nop 1
	v_permlane16_swap_b32 v113, v112
	v_cvt_pk_bf16_f32 v114, v116, v117
	v_cvt_pk_bf16_f32 v115, v118, v119
	v_cvt_pk_bf16_f32 v116, v152, v153
	v_cvt_pk_bf16_f32 v117, v154, v155
	s_waitcnt lgkmcnt(0)
	v_add_f32_e32 v112, v112, v113
	v_xor_b32_e32 v113, 32, v208
	v_cmp_lt_i32_e64 s[6:7], v113, v124
	v_lshl_add_u32 v124, v149, 4, s70
	global_store_dwordx4 v[160:161], v[114:117], off
	v_cndmask_b32_e64 v113, v208, v113, s[6:7]
	v_lshlrev_b32_e32 v126, 2, v113
	v_mov_b32_e32 v113, v112
	s_nop 1
	v_permlane32_swap_b32 v113, v112
	s_and_saveexec_b64 s[6:7], vcc
	s_cbranch_execz .LBB0_994
	s_waitcnt lgkmcnt(0)
	v_add_f32_e32 v112, v112, v113
	ds_write_b32 v124, v112
; __device__ __forceinline__ unsigned cvt_pk_bf16(float lo, float hi) { unsigned r; asm volatile("v_cvt_pk_bf16_f32 %0, %1, %2" : "=v"(r) : "v"(lo), "v"(hi)); return r; }
; #define EPR_LOAD(IT, BUF) do { const unsigned row_ = rb + 128 * ((IT) >> 2) + 16 * ((IT) & 3); _Pragma("unroll") for (int bj = 0; bj < 2; ++bj) \
;             xin[BUF][bj] = *(const u32x4*)(XG + (row_ * DM + cbase + bj * 128)); } while (0)
;     __device__ __forceinline__ void operator()(f32x4 (&acc)[2][2][4][2], const Unit& u, int ui, int wr, int wc, int fr, int fq, int lane, LAS unsigned char* lds) const {
;     ...
;         EPR_LOAD(0, 0);
; #pragma unroll
;         for (int it = 0; it < 8; ++it) {
;             if (it + 1 < 8) EPR_LOAD(it + 1, (it + 1) & 1);
;             __builtin_amdgcn_sched_barrier(0);
;             const int ai = it >> 2, m = it & 3;
;             const unsigned row = rb + 128 * ai + 16 * m;
;             float ss = 0.f;
; #pragma unroll
;             for (int bj = 0; bj < 2; ++bj) {
;                 const u32x4 xw = xin[it & 1][bj];
;                 f32x4 v0, v1;
;                 v0[0] = __builtin_bit_cast(float, xw.x << 16); v0[1] = __builtin_bit_cast(float, xw.x & 0xffff0000u); v0[2] = __builtin_bit_cast(float, xw.y << 16); v0[3] = __builtin_bit_cast(float, xw.y & 0xffff0000u);
;                 v1[0] = __builtin_bit_cast(float, xw.z << 16); v1[1] = __builtin_bit_cast(float, xw.z & 0xffff0000u); v1[2] = __builtin_bit_cast(float, xw.w << 16); v1[3] = __builtin_bit_cast(float, xw.w & 0xffff0000u);
;                 v0 += acc[ai][bj][m][0]; v1 += acc[ai][bj][m][1];
;                 ss += ((v0[0] * v0[0] + v0[1] * v0[1]) + (v0[2] * v0[2] + v0[3] * v0[3])) + ((v1[0] * v1[0] + v1[1] * v1[1]) + (v1[2] * v1[2] + v1[3] * v1[3]));
;                 u32x4 w; w.x = cvt_pk_bf16(v0[0], v0[1]); w.y = cvt_pk_bf16(v0[2], v0[3]); w.z = cvt_pk_bf16(v1[0], v1[1]); w.w = cvt_pk_bf16(v1[2], v1[3]);
;                 *(u32x4*)(XG + (row * DM + cbase + bj * 128)) = w;
;             }
;             ss += __shfl_xor(ss, 16); ss += __shfl_xor(ss, 32);
;             if (fq == 0) red[(128 * ai + 64 * wr + 16 * m + fr) * 4 + wc] = ss;
.LBB0_994:
	s_or_b64 exec, exec, s[6:7]
	v_add_u32_e32 v112, 0x8000, v138
	s_waitcnt lgkmcnt(0)
	v_mov_b32_e32 v113, v189
	v_lshl_add_u64 v[122:123], v[112:113], 1, s[10:11]
	v_add_u32_e32 v112, 0x8080, v138
	v_lshl_add_u64 v[120:121], v[112:113], 1, s[10:11]
	v_lshlrev_b32_e32 v150, 16, v132
	v_and_b32_e32 v151, 0xffff0000, v132
	v_lshlrev_b32_e32 v132, 16, v133
	v_and_b32_e32 v133, 0xffff0000, v133
	v_lshlrev_b32_e32 v152, 16, v134
	v_and_b32_e32 v153, 0xffff0000, v134
	v_lshlrev_b32_e32 v134, 16, v135
	v_and_b32_e32 v135, 0xffff0000, v135
	v_pk_add_f32 v[110:111], v[110:111], v[132:133]
	v_pk_add_f32 v[108:109], v[108:109], v[150:151]
	v_pk_add_f32 v[132:133], v[106:107], v[134:135]
	v_pk_add_f32 v[106:107], v[104:105], v[152:153]
	v_mul_f32_e32 v104, v109, v109
	v_mul_f32_e32 v105, v111, v111
	v_fmac_f32_e32 v104, v108, v108
	v_fmac_f32_e32 v105, v110, v110
	v_add_f32_e32 v104, v104, v105
	v_mul_f32_e32 v105, v107, v107
	v_mul_f32_e32 v127, v133, v133
	v_fmac_f32_e32 v105, v106, v106
	v_fmac_f32_e32 v127, v132, v132
	v_add_f32_e32 v105, v105, v127
	v_add_f32_e32 v127, v104, v105
	v_cvt_pk_bf16_f32 v104, v108, v109
	v_cvt_pk_bf16_f32 v105, v110, v111
	v_lshlrev_b32_e32 v108, 16, v128
	v_and_b32_e32 v109, 0xffff0000, v128
	v_lshlrev_b32_e32 v110, 16, v129
	v_and_b32_e32 v111, 0xffff0000, v129
	v_lshlrev_b32_e32 v128, 16, v130
	v_and_b32_e32 v129, 0xffff0000, v130
	v_pk_add_f32 v[102:103], v[102:103], v[110:111]
	v_pk_add_f32 v[100:101], v[100:101], v[108:109]
	v_lshlrev_b32_e32 v130, 16, v131
	v_and_b32_e32 v131, 0xffff0000, v131
	v_pk_add_f32 v[110:111], v[96:97], v[128:129]
	v_mul_f32_e32 v96, v101, v101
	v_mul_f32_e32 v97, v103, v103
	v_pk_add_f32 v[108:109], v[98:99], v[130:131]
	v_fmac_f32_e32 v96, v100, v100
	v_fmac_f32_e32 v97, v102, v102
	v_add_f32_e32 v96, v96, v97
	v_mul_f32_e32 v97, v111, v111
	v_mul_f32_e32 v98, v109, v109
	v_fmac_f32_e32 v97, v110, v110
	v_fmac_f32_e32 v98, v108, v108
	v_add_f32_e32 v97, v97, v98
	v_add_f32_e32 v96, v96, v97
	v_add_f32_e32 v96, v127, v96
	v_mov_b32_e32 v97, v96
	s_nop 1
	v_permlane16_swap_b32 v97, v96
	v_cvt_pk_bf16_f32 v106, v106, v107
	v_cvt_pk_bf16_f32 v107, v132, v133
	global_store_dwordx4 v[140:141], v[104:107], off
	v_cvt_pk_bf16_f32 v98, v100, v101
	s_waitcnt lgkmcnt(0)
	v_add_f32_e32 v96, v96, v97
	v_mov_b32_e32 v97, v96
	s_nop 1
	v_permlane32_swap_b32 v97, v96
	v_cvt_pk_bf16_f32 v99, v102, v103
	v_cvt_pk_bf16_f32 v100, v110, v111
	v_cvt_pk_bf16_f32 v101, v108, v109
	global_store_dwordx4 v[142:143], v[98:101], off
	s_and_saveexec_b64 s[6:7], vcc
	s_cbranch_execz .LBB0_996
	s_waitcnt lgkmcnt(0)
	v_add_f32_e32 v96, v96, v97
	ds_write_b32 v124, v96 offset:256
.LBB0_996:
	s_or_b64 exec, exec, s[6:7]
	v_add_u32_e32 v96, 0xc000, v138
	s_waitcnt lgkmcnt(0)
	v_mov_b32_e32 v97, v189
	v_lshl_add_u64 v[106:107], v[96:97], 1, s[10:11]
	v_add_u32_e32 v96, 0xc080, v138
	v_lshl_add_u64 v[104:105], v[96:97], 1, s[10:11]
	s_waitcnt vmcnt(15)
	v_lshlrev_b32_e32 v108, 16, v166
	v_and_b32_e32 v109, 0xffff0000, v166
	v_lshlrev_b32_e32 v110, 16, v167
	v_and_b32_e32 v111, 0xffff0000, v167
	v_lshlrev_b32_e32 v116, 16, v168
	v_and_b32_e32 v117, 0xffff0000, v168
	v_lshlrev_b32_e32 v118, 16, v169
	v_and_b32_e32 v119, 0xffff0000, v169
	v_pk_add_f32 v[94:95], v[94:95], v[110:111]
	v_pk_add_f32 v[92:93], v[92:93], v[108:109]
	v_pk_add_f32 v[108:109], v[90:91], v[118:119]
	v_pk_add_f32 v[90:91], v[88:89], v[116:117]
	v_mul_f32_e32 v88, v93, v93
	v_mul_f32_e32 v89, v95, v95
	v_fmac_f32_e32 v88, v92, v92
	v_fmac_f32_e32 v89, v94, v94
	v_add_f32_e32 v88, v88, v89
	v_mul_f32_e32 v89, v91, v91
	v_mul_f32_e32 v110, v109, v109
	v_fmac_f32_e32 v89, v90, v90
	v_fmac_f32_e32 v110, v108, v108
	v_add_f32_e32 v89, v89, v110
	v_add_f32_e32 v116, v88, v89
	v_cvt_pk_bf16_f32 v88, v92, v93
	v_cvt_pk_bf16_f32 v89, v94, v95
	s_waitcnt vmcnt(14)
	v_lshlrev_b32_e32 v92, 16, v170
	v_and_b32_e32 v93, 0xffff0000, v170
	v_lshlrev_b32_e32 v94, 16, v171
	v_and_b32_e32 v95, 0xffff0000, v171
	v_lshlrev_b32_e32 v110, 16, v172
	v_and_b32_e32 v111, 0xffff0000, v172
	v_pk_add_f32 v[86:87], v[86:87], v[94:95]
	v_pk_add_f32 v[84:85], v[84:85], v[92:93]
	v_lshlrev_b32_e32 v112, 16, v173
	v_and_b32_e32 v113, 0xffff0000, v173
	v_pk_add_f32 v[94:95], v[80:81], v[110:111]
	v_mul_f32_e32 v80, v85, v85
	v_mul_f32_e32 v81, v87, v87
	v_pk_add_f32 v[92:93], v[82:83], v[112:113]
	v_fmac_f32_e32 v80, v84, v84
	v_fmac_f32_e32 v81, v86, v86
	v_add_f32_e32 v80, v80, v81
	v_mul_f32_e32 v81, v95, v95
	v_mul_f32_e32 v82, v93, v93
	v_fmac_f32_e32 v81, v94, v94
	v_fmac_f32_e32 v82, v92, v92
	v_add_f32_e32 v81, v81, v82
	v_add_f32_e32 v80, v80, v81
	v_add_f32_e32 v80, v116, v80
	v_mov_b32_e32 v81, v80
	s_nop 1
	v_permlane16_swap_b32 v81, v80
	v_cvt_pk_bf16_f32 v90, v90, v91
	v_cvt_pk_bf16_f32 v91, v108, v109
	global_store_dwordx4 v[122:123], v[88:91], off
	v_cvt_pk_bf16_f32 v82, v84, v85
	s_waitcnt lgkmcnt(0)
	v_add_f32_e32 v80, v80, v81
	v_mov_b32_e32 v81, v80
	s_nop 1
	v_permlane32_swap_b32 v81, v80
	v_cvt_pk_bf16_f32 v83, v86, v87
	v_cvt_pk_bf16_f32 v84, v94, v95
	v_cvt_pk_bf16_f32 v85, v92, v93
	global_store_dwordx4 v[120:121], v[82:85], off
	s_and_saveexec_b64 s[6:7], vcc
	s_cbranch_execz .LBB0_998
	s_waitcnt lgkmcnt(0)
	v_add_f32_e32 v80, v80, v81
	ds_write_b32 v124, v80 offset:512
; __device__ __forceinline__ unsigned cvt_pk_bf16(float lo, float hi) { unsigned r; asm volatile("v_cvt_pk_bf16_f32 %0, %1, %2" : "=v"(r) : "v"(lo), "v"(hi)); return r; }
; #define EPR_LOAD(IT, BUF) do { const unsigned row_ = rb + 128 * ((IT) >> 2) + 16 * ((IT) & 3); _Pragma("unroll") for (int bj = 0; bj < 2; ++bj) \
;             xin[BUF][bj] = *(const u32x4*)(XG + (row_ * DM + cbase + bj * 128)); } while (0)
;     __device__ __forceinline__ void operator()(f32x4 (&acc)[2][2][4][2], const Unit& u, int ui, int wr, int wc, int fr, int fq, int lane, LAS unsigned char* lds) const {
;     ...
;         EPR_LOAD(0, 0);
; #pragma unroll
;         for (int it = 0; it < 8; ++it) {
;             if (it + 1 < 8) EPR_LOAD(it + 1, (it + 1) & 1);
;             __builtin_amdgcn_sched_barrier(0);
;             const int ai = it >> 2, m = it & 3;
;             const unsigned row = rb + 128 * ai + 16 * m;
;             float ss = 0.f;
; #pragma unroll
;             for (int bj = 0; bj < 2; ++bj) {
;                 const u32x4 xw = xin[it & 1][bj];
;                 f32x4 v0, v1;
;                 v0[0] = __builtin_bit_cast(float, xw.x << 16); v0[1] = __builtin_bit_cast(float, xw.x & 0xffff0000u); v0[2] = __builtin_bit_cast(float, xw.y << 16); v0[3] = __builtin_bit_cast(float, xw.y & 0xffff0000u);
;                 v1[0] = __builtin_bit_cast(float, xw.z << 16); v1[1] = __builtin_bit_cast(float, xw.z & 0xffff0000u); v1[2] = __builtin_bit_cast(float, xw.w << 16); v1[3] = __builtin_bit_cast(float, xw.w & 0xffff0000u);
;                 v0 += acc[ai][bj][m][0]; v1 += acc[ai][bj][m][1];
;                 ss += ((v0[0] * v0[0] + v0[1] * v0[1]) + (v0[2] * v0[2] + v0[3] * v0[3])) + ((v1[0] * v1[0] + v1[1] * v1[1]) + (v1[2] * v1[2] + v1[3] * v1[3]));
;                 u32x4 w; w.x = cvt_pk_bf16(v0[0], v0[1]); w.y = cvt_pk_bf16(v0[2], v0[3]); w.z = cvt_pk_bf16(v1[0], v1[1]); w.w = cvt_pk_bf16(v1[2], v1[3]);
;                 *(u32x4*)(XG + (row * DM + cbase + bj * 128)) = w;
;             }
;             ss += __shfl_xor(ss, 16); ss += __shfl_xor(ss, 32);
;             if (fq == 0) red[(128 * ai + 64 * wr + 16 * m + fr) * 4 + wc] = ss;
.LBB0_998:
	s_or_b64 exec, exec, s[6:7]
	v_add_u32_e32 v80, 0x20000, v138
	s_waitcnt lgkmcnt(0)
	v_mov_b32_e32 v81, v189
	v_lshl_add_u64 v[90:91], v[80:81], 1, s[10:11]
	v_add_u32_e32 v80, 0x20080, v138
	v_lshl_add_u64 v[88:89], v[80:81], 1, s[10:11]
	s_waitcnt vmcnt(15)
	v_lshlrev_b32_e32 v92, 16, v174
	v_and_b32_e32 v93, 0xffff0000, v174
	v_lshlrev_b32_e32 v94, 16, v175
	v_and_b32_e32 v95, 0xffff0000, v175
	v_lshlrev_b32_e32 v100, 16, v176
	v_and_b32_e32 v101, 0xffff0000, v176
	v_lshlrev_b32_e32 v102, 16, v177
	v_and_b32_e32 v103, 0xffff0000, v177
	v_pk_add_f32 v[78:79], v[78:79], v[94:95]
	v_pk_add_f32 v[76:77], v[76:77], v[92:93]
	v_pk_add_f32 v[92:93], v[74:75], v[102:103]
	v_pk_add_f32 v[74:75], v[72:73], v[100:101]
	v_mul_f32_e32 v72, v77, v77
	v_mul_f32_e32 v73, v79, v79
	v_fmac_f32_e32 v72, v76, v76
	v_fmac_f32_e32 v73, v78, v78
	v_add_f32_e32 v72, v72, v73
	v_mul_f32_e32 v73, v75, v75
	v_mul_f32_e32 v94, v93, v93
	v_fmac_f32_e32 v73, v74, v74
	v_fmac_f32_e32 v94, v92, v92
	v_add_f32_e32 v73, v73, v94
	v_add_f32_e32 v100, v72, v73
	v_cvt_pk_bf16_f32 v72, v76, v77
	v_cvt_pk_bf16_f32 v73, v78, v79
	s_waitcnt vmcnt(14)
	v_lshlrev_b32_e32 v76, 16, v178
	v_and_b32_e32 v77, 0xffff0000, v178
	v_lshlrev_b32_e32 v78, 16, v179
	v_and_b32_e32 v79, 0xffff0000, v179
	v_lshlrev_b32_e32 v94, 16, v180
	v_and_b32_e32 v95, 0xffff0000, v180
	v_pk_add_f32 v[70:71], v[70:71], v[78:79]
	v_pk_add_f32 v[68:69], v[68:69], v[76:77]
	v_lshlrev_b32_e32 v96, 16, v181
	v_and_b32_e32 v97, 0xffff0000, v181
	v_pk_add_f32 v[78:79], v[64:65], v[94:95]
	v_mul_f32_e32 v64, v69, v69
	v_mul_f32_e32 v65, v71, v71
	v_pk_add_f32 v[76:77], v[66:67], v[96:97]
	v_fmac_f32_e32 v64, v68, v68
	v_fmac_f32_e32 v65, v70, v70
	v_add_f32_e32 v64, v64, v65
	v_mul_f32_e32 v65, v79, v79
	v_mul_f32_e32 v66, v77, v77
	v_fmac_f32_e32 v65, v78, v78
	v_fmac_f32_e32 v66, v76, v76
	v_add_f32_e32 v65, v65, v66
	v_add_f32_e32 v64, v64, v65
	v_add_f32_e32 v64, v100, v64
	v_mov_b32_e32 v65, v64
	s_nop 1
	v_permlane16_swap_b32 v65, v64
	v_cvt_pk_bf16_f32 v74, v74, v75
	v_cvt_pk_bf16_f32 v75, v92, v93
	global_store_dwordx4 v[106:107], v[72:75], off
	v_cvt_pk_bf16_f32 v66, v68, v69
	s_waitcnt lgkmcnt(0)
	v_add_f32_e32 v64, v64, v65
	v_mov_b32_e32 v65, v64
	s_nop 1
	v_permlane32_swap_b32 v65, v64
	v_cvt_pk_bf16_f32 v67, v70, v71
	v_cvt_pk_bf16_f32 v68, v78, v79
	v_cvt_pk_bf16_f32 v69, v76, v77
	global_store_dwordx4 v[104:105], v[66:69], off
	s_and_saveexec_b64 s[6:7], vcc
	s_cbranch_execz .LBB0_1000
	s_waitcnt lgkmcnt(0)
	v_add_f32_e32 v64, v64, v65
	ds_write_b32 v124, v64 offset:768
.LBB0_1000:
	s_or_b64 exec, exec, s[6:7]
	v_add_u32_e32 v64, 0x24000, v138
	s_waitcnt lgkmcnt(0)
	v_mov_b32_e32 v65, v189
	v_lshl_add_u64 v[74:75], v[64:65], 1, s[10:11]
	v_add_u32_e32 v64, 0x24080, v138
	v_lshl_add_u64 v[72:73], v[64:65], 1, s[10:11]
	s_waitcnt vmcnt(15)
	v_lshlrev_b32_e32 v76, 16, v182
	v_and_b32_e32 v77, 0xffff0000, v182
	v_lshlrev_b32_e32 v78, 16, v183
	v_and_b32_e32 v79, 0xffff0000, v183
	v_lshlrev_b32_e32 v84, 16, v184
	v_and_b32_e32 v85, 0xffff0000, v184
	v_lshlrev_b32_e32 v86, 16, v185
	v_and_b32_e32 v87, 0xffff0000, v185
	v_pk_add_f32 v[62:63], v[62:63], v[78:79]
	v_pk_add_f32 v[60:61], v[60:61], v[76:77]
	v_pk_add_f32 v[76:77], v[58:59], v[86:87]
	v_pk_add_f32 v[58:59], v[56:57], v[84:85]
	v_mul_f32_e32 v56, v61, v61
	v_mul_f32_e32 v57, v63, v63
	v_fmac_f32_e32 v56, v60, v60
	v_fmac_f32_e32 v57, v62, v62
	v_add_f32_e32 v56, v56, v57
	v_mul_f32_e32 v57, v59, v59
	v_mul_f32_e32 v78, v77, v77
	v_fmac_f32_e32 v57, v58, v58
	v_fmac_f32_e32 v78, v76, v76
	v_add_f32_e32 v57, v57, v78
	v_add_f32_e32 v84, v56, v57
	v_cvt_pk_bf16_f32 v56, v60, v61
	v_cvt_pk_bf16_f32 v57, v62, v63
	s_waitcnt vmcnt(14)
	v_lshlrev_b32_e32 v60, 16, v194
	v_and_b32_e32 v61, 0xffff0000, v194
	v_lshlrev_b32_e32 v62, 16, v195
	v_and_b32_e32 v63, 0xffff0000, v195
	v_lshlrev_b32_e32 v78, 16, v196
	v_and_b32_e32 v79, 0xffff0000, v196
	v_pk_add_f32 v[54:55], v[54:55], v[62:63]
	v_pk_add_f32 v[52:53], v[52:53], v[60:61]
	v_lshlrev_b32_e32 v80, 16, v197
	v_and_b32_e32 v81, 0xffff0000, v197
	v_pk_add_f32 v[62:63], v[48:49], v[78:79]
	v_mul_f32_e32 v48, v53, v53
	v_mul_f32_e32 v49, v55, v55
	v_pk_add_f32 v[60:61], v[50:51], v[80:81]
	v_fmac_f32_e32 v48, v52, v52
	v_fmac_f32_e32 v49, v54, v54
	v_add_f32_e32 v48, v48, v49
	v_mul_f32_e32 v49, v63, v63
	v_mul_f32_e32 v50, v61, v61
	v_fmac_f32_e32 v49, v62, v62
	v_fmac_f32_e32 v50, v60, v60
	v_add_f32_e32 v49, v49, v50
	v_add_f32_e32 v48, v48, v49
	v_add_f32_e32 v48, v84, v48
	v_mov_b32_e32 v49, v48
	s_nop 1
	v_permlane16_swap_b32 v49, v48
	v_cvt_pk_bf16_f32 v58, v58, v59
	v_cvt_pk_bf16_f32 v59, v76, v77
	global_store_dwordx4 v[90:91], v[56:59], off
	v_cvt_pk_bf16_f32 v50, v52, v53
	s_waitcnt lgkmcnt(0)
	v_add_f32_e32 v48, v48, v49
	v_mov_b32_e32 v49, v48
	s_nop 1
	v_permlane32_swap_b32 v49, v48
	v_cvt_pk_bf16_f32 v51, v54, v55
	v_cvt_pk_bf16_f32 v52, v62, v63
	v_cvt_pk_bf16_f32 v53, v60, v61
	global_store_dwordx4 v[88:89], v[50:53], off
	s_and_saveexec_b64 s[6:7], vcc
	s_cbranch_execz .LBB0_1002
	s_waitcnt lgkmcnt(0)
	v_add_f32_e32 v48, v48, v49
	ds_write_b32 v124, v48 offset:2048
; __device__ __forceinline__ unsigned cvt_pk_bf16(float lo, float hi) { unsigned r; asm volatile("v_cvt_pk_bf16_f32 %0, %1, %2" : "=v"(r) : "v"(lo), "v"(hi)); return r; }
; #define EPR_LOAD(IT, BUF) do { const unsigned row_ = rb + 128 * ((IT) >> 2) + 16 * ((IT) & 3); _Pragma("unroll") for (int bj = 0; bj < 2; ++bj) \
;             xin[BUF][bj] = *(const u32x4*)(XG + (row_ * DM + cbase + bj * 128)); } while (0)
;     __device__ __forceinline__ void operator()(f32x4 (&acc)[2][2][4][2], const Unit& u, int ui, int wr, int wc, int fr, int fq, int lane, LAS unsigned char* lds) const {
;     ...
;         EPR_LOAD(0, 0);
; #pragma unroll
;         for (int it = 0; it < 8; ++it) {
;             if (it + 1 < 8) EPR_LOAD(it + 1, (it + 1) & 1);
;             __builtin_amdgcn_sched_barrier(0);
;             const int ai = it >> 2, m = it & 3;
;             const unsigned row = rb + 128 * ai + 16 * m;
;             float ss = 0.f;
; #pragma unroll
;             for (int bj = 0; bj < 2; ++bj) {
;                 const u32x4 xw = xin[it & 1][bj];
;                 f32x4 v0, v1;
;                 v0[0] = __builtin_bit_cast(float, xw.x << 16); v0[1] = __builtin_bit_cast(float, xw.x & 0xffff0000u); v0[2] = __builtin_bit_cast(float, xw.y << 16); v0[3] = __builtin_bit_cast(float, xw.y & 0xffff0000u);
;                 v1[0] = __builtin_bit_cast(float, xw.z << 16); v1[1] = __builtin_bit_cast(float, xw.z & 0xffff0000u); v1[2] = __builtin_bit_cast(float, xw.w << 16); v1[3] = __builtin_bit_cast(float, xw.w & 0xffff0000u);
;                 v0 += acc[ai][bj][m][0]; v1 += acc[ai][bj][m][1];
;                 ss += ((v0[0] * v0[0] + v0[1] * v0[1]) + (v0[2] * v0[2] + v0[3] * v0[3])) + ((v1[0] * v1[0] + v1[1] * v1[1]) + (v1[2] * v1[2] + v1[3] * v1[3]));
;                 u32x4 w; w.x = cvt_pk_bf16(v0[0], v0[1]); w.y = cvt_pk_bf16(v0[2], v0[3]); w.z = cvt_pk_bf16(v1[0], v1[1]); w.w = cvt_pk_bf16(v1[2], v1[3]);
;                 *(u32x4*)(XG + (row * DM + cbase + bj * 128)) = w;
;             }
;             ss += __shfl_xor(ss, 16); ss += __shfl_xor(ss, 32);
;             if (fq == 0) red[(128 * ai + 64 * wr + 16 * m + fr) * 4 + wc] = ss;
.LBB0_1002:
	s_or_b64 exec, exec, s[6:7]
	v_add_u32_e32 v48, 0x28000, v138
	s_waitcnt lgkmcnt(0)
	v_mov_b32_e32 v49, v189
	v_lshl_add_u64 v[58:59], v[48:49], 1, s[10:11]
	v_add_u32_e32 v48, 0x28080, v138
	v_lshl_add_u64 v[56:57], v[48:49], 1, s[10:11]
	s_waitcnt vmcnt(15)
	v_lshlrev_b32_e32 v60, 16, v198
	v_and_b32_e32 v61, 0xffff0000, v198
	v_lshlrev_b32_e32 v62, 16, v199
	v_and_b32_e32 v63, 0xffff0000, v199
	v_lshlrev_b32_e32 v68, 16, v200
	v_and_b32_e32 v69, 0xffff0000, v200
	v_lshlrev_b32_e32 v70, 16, v201
	v_and_b32_e32 v71, 0xffff0000, v201
	v_pk_add_f32 v[46:47], v[46:47], v[62:63]
	v_pk_add_f32 v[44:45], v[44:45], v[60:61]
	v_pk_add_f32 v[60:61], v[42:43], v[70:71]
	v_pk_add_f32 v[42:43], v[40:41], v[68:69]
	v_mul_f32_e32 v40, v45, v45
	v_mul_f32_e32 v41, v47, v47
	v_fmac_f32_e32 v40, v44, v44
	v_fmac_f32_e32 v41, v46, v46
	v_add_f32_e32 v40, v40, v41
	v_mul_f32_e32 v41, v43, v43
	v_mul_f32_e32 v62, v61, v61
	v_fmac_f32_e32 v41, v42, v42
	v_fmac_f32_e32 v62, v60, v60
	v_add_f32_e32 v41, v41, v62
	v_add_f32_e32 v68, v40, v41
	v_cvt_pk_bf16_f32 v40, v44, v45
	v_cvt_pk_bf16_f32 v41, v46, v47
	s_waitcnt vmcnt(14)
	v_lshlrev_b32_e32 v44, 16, v202
	v_and_b32_e32 v45, 0xffff0000, v202
	v_lshlrev_b32_e32 v46, 16, v203
	v_and_b32_e32 v47, 0xffff0000, v203
	v_lshlrev_b32_e32 v62, 16, v204
	v_and_b32_e32 v63, 0xffff0000, v204
	v_pk_add_f32 v[38:39], v[38:39], v[46:47]
	v_pk_add_f32 v[36:37], v[36:37], v[44:45]
	v_lshlrev_b32_e32 v64, 16, v205
	v_and_b32_e32 v65, 0xffff0000, v205
	v_pk_add_f32 v[46:47], v[32:33], v[62:63]
	v_mul_f32_e32 v32, v37, v37
	v_mul_f32_e32 v33, v39, v39
	v_pk_add_f32 v[44:45], v[34:35], v[64:65]
	v_fmac_f32_e32 v32, v36, v36
	v_fmac_f32_e32 v33, v38, v38
	v_add_f32_e32 v32, v32, v33
	v_mul_f32_e32 v33, v47, v47
	v_mul_f32_e32 v34, v45, v45
	v_fmac_f32_e32 v33, v46, v46
	v_fmac_f32_e32 v34, v44, v44
	v_add_f32_e32 v33, v33, v34
	v_add_f32_e32 v32, v32, v33
	v_add_f32_e32 v32, v68, v32
	v_mov_b32_e32 v33, v32
	s_nop 1
	v_permlane16_swap_b32 v33, v32
	v_cvt_pk_bf16_f32 v42, v42, v43
	v_cvt_pk_bf16_f32 v43, v60, v61
	global_store_dwordx4 v[74:75], v[40:43], off
	v_cvt_pk_bf16_f32 v34, v36, v37
	s_waitcnt lgkmcnt(0)
	v_add_f32_e32 v32, v32, v33
	v_mov_b32_e32 v33, v32
	s_nop 1
	v_permlane32_swap_b32 v33, v32
	v_cvt_pk_bf16_f32 v35, v38, v39
	v_cvt_pk_bf16_f32 v36, v46, v47
	v_cvt_pk_bf16_f32 v37, v44, v45
	global_store_dwordx4 v[72:73], v[34:37], off
	s_and_saveexec_b64 s[6:7], vcc
	s_cbranch_execz .LBB0_1004
	s_waitcnt lgkmcnt(0)
	v_add_f32_e32 v32, v32, v33
	ds_write_b32 v124, v32 offset:2304
; __device__ __forceinline__ unsigned cvt_pk_bf16(float lo, float hi) { unsigned r; asm volatile("v_cvt_pk_bf16_f32 %0, %1, %2" : "=v"(r) : "v"(lo), "v"(hi)); return r; }
; #define EPR_LOAD(IT, BUF) do { const unsigned row_ = rb + 128 * ((IT) >> 2) + 16 * ((IT) & 3); _Pragma("unroll") for (int bj = 0; bj < 2; ++bj) \
;             xin[BUF][bj] = *(const u32x4*)(XG + (row_ * DM + cbase + bj * 128)); } while (0)
;     __device__ __forceinline__ void operator()(f32x4 (&acc)[2][2][4][2], const Unit& u, int ui, int wr, int wc, int fr, int fq, int lane, LAS unsigned char* lds) const {
;     ...
;         EPR_LOAD(0, 0);
; #pragma unroll
;         for (int it = 0; it < 8; ++it) {
;             if (it + 1 < 8) EPR_LOAD(it + 1, (it + 1) & 1);
;             __builtin_amdgcn_sched_barrier(0);
;             const int ai = it >> 2, m = it & 3;
;             const unsigned row = rb + 128 * ai + 16 * m;
;             float ss = 0.f;
; #pragma unroll
;             for (int bj = 0; bj < 2; ++bj) {
;                 const u32x4 xw = xin[it & 1][bj];
;                 f32x4 v0, v1;
;                 v0[0] = __builtin_bit_cast(float, xw.x << 16); v0[1] = __builtin_bit_cast(float, xw.x & 0xffff0000u); v0[2] = __builtin_bit_cast(float, xw.y << 16); v0[3] = __builtin_bit_cast(float, xw.y & 0xffff0000u);
;                 v1[0] = __builtin_bit_cast(float, xw.z << 16); v1[1] = __builtin_bit_cast(float, xw.z & 0xffff0000u); v1[2] = __builtin_bit_cast(float, xw.w << 16); v1[3] = __builtin_bit_cast(float, xw.w & 0xffff0000u);
;                 v0 += acc[ai][bj][m][0]; v1 += acc[ai][bj][m][1];
;                 ss += ((v0[0] * v0[0] + v0[1] * v0[1]) + (v0[2] * v0[2] + v0[3] * v0[3])) + ((v1[0] * v1[0] + v1[1] * v1[1]) + (v1[2] * v1[2] + v1[3] * v1[3]));
;                 u32x4 w; w.x = cvt_pk_bf16(v0[0], v0[1]); w.y = cvt_pk_bf16(v0[2], v0[3]); w.z = cvt_pk_bf16(v1[0], v1[1]); w.w = cvt_pk_bf16(v1[2], v1[3]);
;                 *(u32x4*)(XG + (row * DM + cbase + bj * 128)) = w;
;             }
;             ss += __shfl_xor(ss, 16); ss += __shfl_xor(ss, 32);
;             if (fq == 0) red[(128 * ai + 64 * wr + 16 * m + fr) * 4 + wc] = ss;
.LBB0_1004:
	s_or_b64 exec, exec, s[6:7]
	v_add_u32_e32 v32, 0x2c000, v138
	s_waitcnt lgkmcnt(0)
	v_mov_b32_e32 v33, v189
	v_lshl_add_u64 v[42:43], v[32:33], 1, s[10:11]
	v_add_u32_e32 v32, 0x2c080, v138
	v_lshl_add_u64 v[40:41], v[32:33], 1, s[10:11]
	s_waitcnt vmcnt(15)
	v_lshlrev_b32_e32 v44, 16, v212
	v_and_b32_e32 v45, 0xffff0000, v212
	v_lshlrev_b32_e32 v46, 16, v213
	v_and_b32_e32 v47, 0xffff0000, v213
	v_lshlrev_b32_e32 v52, 16, v214
	v_and_b32_e32 v53, 0xffff0000, v214
	v_lshlrev_b32_e32 v54, 16, v215
	v_and_b32_e32 v55, 0xffff0000, v215
	v_pk_add_f32 v[30:31], v[30:31], v[46:47]
	v_pk_add_f32 v[28:29], v[28:29], v[44:45]
	v_pk_add_f32 v[44:45], v[26:27], v[54:55]
	v_pk_add_f32 v[26:27], v[24:25], v[52:53]
	v_mul_f32_e32 v24, v29, v29
	v_mul_f32_e32 v25, v31, v31
	v_fmac_f32_e32 v24, v28, v28
	v_fmac_f32_e32 v25, v30, v30
	v_add_f32_e32 v24, v24, v25
	v_mul_f32_e32 v25, v27, v27
	v_mul_f32_e32 v46, v45, v45
	v_fmac_f32_e32 v25, v26, v26
	v_fmac_f32_e32 v46, v44, v44
	v_add_f32_e32 v25, v25, v46
	v_add_f32_e32 v52, v24, v25
	v_cvt_pk_bf16_f32 v24, v28, v29
	v_cvt_pk_bf16_f32 v25, v30, v31
	s_waitcnt vmcnt(14)
	v_lshlrev_b32_e32 v28, 16, v216
	v_and_b32_e32 v29, 0xffff0000, v216
	v_lshlrev_b32_e32 v30, 16, v217
	v_and_b32_e32 v31, 0xffff0000, v217
	v_lshlrev_b32_e32 v46, 16, v218
	v_and_b32_e32 v47, 0xffff0000, v218
	v_pk_add_f32 v[22:23], v[22:23], v[30:31]
	v_pk_add_f32 v[20:21], v[20:21], v[28:29]
	v_lshlrev_b32_e32 v48, 16, v219
	v_and_b32_e32 v49, 0xffff0000, v219
	v_pk_add_f32 v[30:31], v[16:17], v[46:47]
	v_mul_f32_e32 v16, v21, v21
	v_mul_f32_e32 v17, v23, v23
	v_pk_add_f32 v[28:29], v[18:19], v[48:49]
	v_fmac_f32_e32 v16, v20, v20
	v_fmac_f32_e32 v17, v22, v22
	v_add_f32_e32 v16, v16, v17
	v_mul_f32_e32 v17, v31, v31
	v_mul_f32_e32 v18, v29, v29
	v_fmac_f32_e32 v17, v30, v30
	v_fmac_f32_e32 v18, v28, v28
	v_add_f32_e32 v17, v17, v18
	v_add_f32_e32 v16, v16, v17
	v_add_f32_e32 v16, v52, v16
	v_mov_b32_e32 v17, v16
	s_nop 1
	v_permlane16_swap_b32 v17, v16
	v_cvt_pk_bf16_f32 v26, v26, v27
	v_cvt_pk_bf16_f32 v27, v44, v45
	global_store_dwordx4 v[58:59], v[24:27], off
	v_cvt_pk_bf16_f32 v18, v20, v21
	s_waitcnt lgkmcnt(0)
	v_add_f32_e32 v16, v16, v17
	v_mov_b32_e32 v17, v16
	s_nop 1
	v_permlane32_swap_b32 v17, v16
	v_cvt_pk_bf16_f32 v19, v22, v23
	v_cvt_pk_bf16_f32 v20, v30, v31
	v_cvt_pk_bf16_f32 v21, v28, v29
	global_store_dwordx4 v[56:57], v[18:21], off
	s_and_saveexec_b64 s[6:7], vcc
	s_cbranch_execz .LBB0_1006
	s_waitcnt lgkmcnt(0)
	v_add_f32_e32 v16, v16, v17
	ds_write_b32 v124, v16 offset:2560
.LBB0_1006:
	s_or_b64 exec, exec, s[6:7]
	s_waitcnt vmcnt(15)
	v_lshlrev_b32_e32 v16, 16, v220
	s_waitcnt lgkmcnt(0)
	v_and_b32_e32 v17, 0xffff0000, v220
	v_lshlrev_b32_e32 v18, 16, v221
	v_and_b32_e32 v19, 0xffff0000, v221
	v_lshlrev_b32_e32 v20, 16, v222
	v_and_b32_e32 v21, 0xffff0000, v222
	v_lshlrev_b32_e32 v22, 16, v223
	v_and_b32_e32 v23, 0xffff0000, v223
	v_pk_add_f32 v[14:15], v[14:15], v[18:19]
	v_pk_add_f32 v[12:13], v[12:13], v[16:17]
	v_pk_add_f32 v[16:17], v[10:11], v[22:23]
	v_pk_add_f32 v[10:11], v[8:9], v[20:21]
	v_mul_f32_e32 v8, v13, v13
	v_mul_f32_e32 v9, v15, v15
	v_fmac_f32_e32 v8, v12, v12
	v_fmac_f32_e32 v9, v14, v14
	v_add_f32_e32 v8, v8, v9
	v_mul_f32_e32 v9, v11, v11
	v_mul_f32_e32 v18, v17, v17
	v_fmac_f32_e32 v9, v10, v10
	v_fmac_f32_e32 v18, v16, v16
	v_add_f32_e32 v9, v9, v18
	v_add_f32_e32 v22, v8, v9
	v_cvt_pk_bf16_f32 v8, v12, v13
	v_cvt_pk_bf16_f32 v9, v14, v15
	s_waitcnt vmcnt(14)
	v_lshlrev_b32_e32 v12, 16, v224
	v_and_b32_e32 v13, 0xffff0000, v224
	v_lshlrev_b32_e32 v14, 16, v225
	v_and_b32_e32 v15, 0xffff0000, v225
	v_lshlrev_b32_e32 v18, 16, v226
	v_and_b32_e32 v19, 0xffff0000, v226
	v_pk_add_f32 v[6:7], v[6:7], v[14:15]
	v_pk_add_f32 v[4:5], v[4:5], v[12:13]
	v_lshlrev_b32_e32 v20, 16, v227
	v_and_b32_e32 v21, 0xffff0000, v227
	v_pk_add_f32 v[14:15], v[0:1], v[18:19]
	v_mul_f32_e32 v0, v5, v5
	v_mul_f32_e32 v1, v7, v7
	v_pk_add_f32 v[12:13], v[2:3], v[20:21]
	v_fmac_f32_e32 v0, v4, v4
	v_fmac_f32_e32 v1, v6, v6
	v_add_f32_e32 v0, v0, v1
	v_mul_f32_e32 v1, v15, v15
	v_mul_f32_e32 v2, v13, v13
	v_fmac_f32_e32 v1, v14, v14
	v_fmac_f32_e32 v2, v12, v12
	v_add_f32_e32 v1, v1, v2
	v_add_f32_e32 v0, v0, v1
	v_add_f32_e32 v0, v22, v0
	v_mov_b32_e32 v1, v0
	s_nop 1
	v_permlane16_swap_b32 v1, v0
	v_cvt_pk_bf16_f32 v10, v10, v11
	v_cvt_pk_bf16_f32 v11, v16, v17
	global_store_dwordx4 v[42:43], v[8:11], off
	v_cvt_pk_bf16_f32 v2, v4, v5
	s_waitcnt lgkmcnt(0)
	v_add_f32_e32 v0, v0, v1
	v_mov_b32_e32 v1, v0
	s_nop 1
	v_permlane32_swap_b32 v1, v0
	v_cvt_pk_bf16_f32 v3, v6, v7
	v_cvt_pk_bf16_f32 v4, v14, v15
	v_cvt_pk_bf16_f32 v5, v12, v13
	global_store_dwordx4 v[40:41], v[2:5], off
	s_and_saveexec_b64 s[6:7], vcc
	s_cbranch_execz .LBB0_1008
	s_waitcnt lgkmcnt(0)
	v_add_f32_e32 v0, v0, v1
	ds_write_b32 v124, v0 offset:2816
